# v23 + lazy-rescale threshold on all attention paths, one lgkmcnt wait per MFMA pair, L1 invalidate issued at arrival in XCC-local barriers
# speedup vs baseline: 1.0386x; 1.0143x over previous
.LBB0_1113:
	s_mov_b64 s[18:19], -1
	s_and_b64 vcc, exec, s[16:17]
	s_cbranch_vccz .LBB0_1103
	s_lshl_b32 s16, s20, 4
	s_and_b32 s18, s16, 0x70
	s_bfe_u32 s19, s20, 0x40003
	s_and_b32 s21, s20, 0x7f
	s_load_dwordx2 s[16:17], s[14:15], 0x88
	s_or_b32 s22, s18, s19
	s_and_b64 s[18:19], s[82:83], exec
	v_readlane_b32 s18, v254, 63
	v_readlane_b32 s19, v255, 0
	s_cselect_b32 s62, s22, s21
	s_lshl_b64 s[18:19], s[18:19], 2
	s_waitcnt lgkmcnt(0)
	s_add_u32 s16, s16, s18
	s_addc_u32 s17, s17, s19
	s_cmpk_gt_u32 s20, 0x7f
	s_mov_b64 s[18:19], -1
	s_cbranch_scc0 .LBB0_1169
	s_ashr_i32 s63, s20, 7
	s_mov_b64 s[22:23], -1
	s_mov_b64 s[18:19], 0
	s_cmp_lt_i32 s63, 2
	s_mov_b64 s[20:21], 0
	s_cbranch_scc1 .LBB0_1129
	s_cmp_eq_u32 s63, 2
	s_mov_b64 s[20:21], -1
	s_cbranch_scc0 .LBB0_1137
	s_lshr_b32 s20, s62, 3
	s_lshl_b32 s22, s62, 7
	s_lshl_b32 s21, s20, 8
	s_and_b32 s22, s22, 0x80
	s_or_b32 s26, s21, s22
	s_lshl_b32 s21, s26, 10
	s_add_u32 s22, s37, s21
	s_addc_u32 s23, s38, 0
	s_lshl_b32 s21, s62, 6
	s_and_b32 s27, s21, 0x180
	v_mov_b32_e32 v158, v244
	s_or_b32 s66, s27, 64
	s_lshl_b32 s21, s20, 18
	s_add_u32 s24, s39, s21
	v_add_u32_e32 v14, 0x200, v158
	v_ashrrev_i32_e32 v0, 31, v158
	v_ashrrev_i32_e32 v2, 31, v14
	s_addc_u32 s25, s40, 0
	s_lshl_b32 s20, s27, 1
	v_lshrrev_b32_e32 v0, 28, v0
	v_lshrrev_b32_e32 v2, 28, v2
	s_add_u32 s24, s24, s20
	v_add_u32_e32 v0, v158, v0
	v_add_u32_e32 v2, v14, v2
	s_addc_u32 s25, s25, 0
	v_ashrrev_i32_e32 v146, 4, v0
	v_and_b32_e32 v0, -16, v0
	v_ashrrev_i32_e32 v148, 4, v2
	v_and_b32_e32 v2, -16, v2
	s_add_u32 s21, s41, s21
	v_sub_u32_e32 v22, v158, v0
	v_sub_u32_e32 v23, v14, v2
	s_addc_u32 s65, s44, 0
	s_lshl_b32 s64, s27, 9
	v_ashrrev_i32_e32 v147, 31, v146
	v_lshlrev_b32_e32 v168, 3, v22
	v_ashrrev_i32_e32 v149, 31, v148
	v_lshlrev_b32_e32 v170, 3, v23
	s_add_u32 s64, s21, s64
	v_readfirstlane_b32 s70, v158
	v_lshlrev_b64 v[150:151], 10, v[146:147]
	v_ashrrev_i32_e32 v169, 31, v168
	v_lshlrev_b64 v[154:155], 10, v[148:149]
	v_ashrrev_i32_e32 v171, 31, v170
	s_addc_u32 s65, s65, 0
	v_lshl_add_u64 v[0:1], s[24:25], 0, v[150:151]
	v_lshlrev_b64 v[152:153], 1, v[168:169]
	v_lshl_add_u64 v[2:3], s[24:25], 0, v[154:155]
	v_lshlrev_b64 v[156:157], 1, v[170:171]
	v_lshlrev_b32_e32 v8, 4, v158
	v_ashrrev_i32_e32 v16, 3, v158
	v_ashrrev_i32_e32 v18, 3, v14
	s_lshl_b32 s21, s70, 8
	v_and_b32_e32 v36, 31, v158
	v_lshl_add_u64 v[0:1], v[0:1], 0, v[152:153]
	v_lshl_add_u64 v[4:5], v[2:3], 0, v[156:157]
	v_and_b32_e32 v166, 0x70, v8
	v_mov_b32_e32 v167, v129
	v_ashrrev_i32_e32 v17, 31, v16
	v_ashrrev_i32_e32 v19, 31, v18
	s_and_b32 s21, s21, 0xc000
	global_load_dwordx4 v[0:3], v[0:1], off
	s_nop 0
	global_load_dwordx4 v[4:7], v[4:5], off
	v_lshl_add_u64 v[12:13], s[64:65], 0, v[166:167]
	v_lshlrev_b64 v[8:9], 9, v[16:17]
	v_lshlrev_b64 v[14:15], 9, v[18:19]
	v_lshl_or_b32 v17, v36, 9, s21
	v_lshl_add_u64 v[172:173], v[12:13], 0, v[8:9]
	v_lshl_add_u64 v[174:175], v[12:13], 0, v[14:15]
	v_lshlrev_b32_e32 v128, 1, v17
	s_cmpk_lt_u32 s70, 0x100
	global_load_dwordx4 v[8:11], v[172:173], off
	global_load_dwordx4 v[12:15], v[174:175], off
	v_lshl_add_u64 v[20:21], s[22:23], 0, v[128:129]
	s_cselect_b64 s[22:23], -1, 0
	s_and_b64 s[64:65], s[22:23], exec
	s_cselect_b32 s27, s27, s66
	v_bfe_u32 v37, v158, 5, 1
	s_lshl_b32 s68, s27, 1
	v_lshlrev_b32_e32 v162, 4, v37
	v_lshl_add_u64 v[20:21], v[20:21], 0, s[68:69]
	v_mov_b32_e32 v163, v129
	v_lshl_add_u64 v[20:21], v[20:21], 0, v[162:163]
	global_load_dwordx4 v[130:133], v[20:21], off
	global_load_dwordx4 v[134:137], v[20:21], off offset:32
	global_load_dwordx4 v[138:141], v[20:21], off offset:64
	global_load_dwordx4 v[142:145], v[20:21], off offset:96
	s_movk_i32 s65, 0x110
	v_mul_lo_u32 v165, v146, s65
	v_lshlrev_b32_e32 v167, 4, v22
	v_add3_u32 v38, 0, v165, v167
	v_mul_lo_u32 v176, v148, s65
	s_movk_i32 s65, 0x90
	s_ashr_i32 s64, s70, 8
	v_mul_lo_u32 v178, v16, s65
	v_mul_lo_u32 v179, v18, s65
	v_mul_u32_u24_e32 v17, 0x110, v36
	s_lshl_b32 s27, s64, 7
	v_lshlrev_b32_e32 v177, 4, v23
	v_add3_u32 v39, 0, v176, v177
	s_add_u32 s70, s24, 0x10000
	s_addc_u32 s71, s25, 0
	v_and_b32_e32 v43, 64, v248
	v_xor_b32_e32 v42, 32, v248
	v_add_u32_e32 v43, 64, v43
	v_cmp_lt_i32_e32 vcc, v42, v43
	v_lshlrev_b32_e32 v164, 3, v37
	s_waitcnt vmcnt(7)
	ds_write_b128 v38, v[0:3]
	v_add_u32_e32 v0, 0, v166
	v_add_u32_e32 v40, v0, v178
	v_add_u32_e32 v41, v0, v179
	v_add_u32_e32 v0, 0, v162
	v_add3_u32 v180, v0, v17, s27
	s_waitcnt vmcnt(6)
	ds_write_b128 v39, v[4:7]
	v_cndmask_b32_e32 v42, v248, v42, vcc
	v_lshlrev_b32_e32 v163, 2, v42
	s_waitcnt vmcnt(5)
	ds_write_b128 v40, v[8:11] offset:17408
	s_waitcnt vmcnt(4)
	ds_write_b128 v41, v[12:15] offset:17408
	s_waitcnt lgkmcnt(0)
	s_barrier
	ds_read_b128 v[0:3], v180
	ds_read_b128 v[16:19], v180 offset:32
	s_waitcnt vmcnt(3) lgkmcnt(1)
	v_mfma_f32_32x32x16_bf16 v[0:15], v[0:3], v[130:133], 0
	ds_read_b128 v[20:23], v180 offset:8704
	ds_read_b128 v[24:27], v180 offset:8736
	s_waitcnt vmcnt(2) lgkmcnt(2)
	v_mfma_f32_32x32x16_bf16 v[0:15], v[16:19], v[134:137], v[0:15]
	s_waitcnt lgkmcnt(1)
	v_mfma_f32_32x32x16_bf16 v[112:127], v[20:23], v[130:133], 0
	ds_read_b128 v[16:19], v180 offset:64
	ds_read_b128 v[20:23], v180 offset:96
	s_waitcnt vmcnt(1) lgkmcnt(1)
	v_mfma_f32_32x32x16_bf16 v[0:15], v[16:19], v[138:141], v[0:15]
	ds_read_b128 v[16:19], v180 offset:8768
	v_mfma_f32_32x32x16_bf16 v[112:127], v[24:27], v[134:137], v[112:127]
	ds_read_b128 v[24:27], v180 offset:8800
	s_waitcnt lgkmcnt(1)
	v_mfma_f32_32x32x16_bf16 v[112:127], v[16:19], v[138:141], v[112:127]
	v_lshl_add_u64 v[16:17], s[70:71], 0, v[150:151]
	v_lshl_add_u64 v[18:19], s[70:71], 0, v[154:155]
	v_lshl_add_u64 v[16:17], v[16:17], 0, v[152:153]
	v_lshl_add_u64 v[28:29], v[18:19], 0, v[156:157]
	global_load_dwordx4 v[16:19], v[16:17], off
	s_nop 0
	global_load_dwordx4 v[28:31], v[28:29], off
	s_add_u32 s70, s24, 0x20000
	s_addc_u32 s71, s25, 0
	s_waitcnt vmcnt(2)
	v_mfma_f32_32x32x16_bf16 v[0:15], v[20:23], v[142:145], v[0:15]
	global_load_dwordx4 v[20:23], v[172:173], off offset:128
	global_load_dwordx4 v[32:35], v[174:175], off offset:128
	s_waitcnt lgkmcnt(0)
	v_mfma_f32_32x32x16_bf16 v[112:127], v[24:27], v[142:145], v[112:127]
	s_nop 15
	s_nop 7
	s_waitcnt vmcnt(3)
	ds_write_b128 v38, v[16:19] offset:36864
	s_waitcnt vmcnt(2)
	ds_write_b128 v39, v[28:31] offset:36864
	s_waitcnt vmcnt(1)
	ds_write_b128 v40, v[20:23] offset:54272
	s_waitcnt vmcnt(0)
	ds_write_b128 v41, v[32:35] offset:54272
	v_max3_f32 v24, v0, v1, v112
	s_waitcnt lgkmcnt(0)
	v_max3_f32 v24, v24, v113, v2
	s_barrier
	v_max3_f32 v24, v24, v114, v114
	s_nop 0
	v_max3_f32 v24, v24, v3, v115
	ds_read_b128 v[16:19], v180 offset:36864
	ds_read_b128 v[20:23], v180 offset:36896
	v_max3_f32 v24, v24, v4, v116
	s_nop 0
	v_max3_f32 v24, v24, v5, v117
	s_nop 0
	v_max3_f32 v24, v24, v6, v118
	s_nop 0
	v_max3_f32 v24, v24, v7, v119
	s_nop 0
	v_max3_f32 v24, v24, v8, v120
	s_nop 0
	v_max3_f32 v24, v24, v9, v121
	s_nop 0
	v_max3_f32 v24, v24, v10, v122
	s_nop 0
	v_max3_f32 v24, v24, v11, v123
	s_nop 0
	v_max3_f32 v24, v24, v12, v124
	s_nop 0
	v_max3_f32 v24, v24, v13, v125
	s_nop 0
	v_max3_f32 v24, v24, v14, v126
	s_nop 0
	v_max3_f32 v24, v24, v15, v127
	ds_bpermute_b32 v25, v163, v24
	v_max_f32_e32 v24, v24, v24
	s_waitcnt lgkmcnt(0)
	v_max_f32_e32 v25, v25, v25
	v_max_f32_e32 v159, v24, v25
	v_add_f32_e32 v181, 0, v159
	v_xor_b32_e32 v64, 0x80000000, v181
	v_mov_b32_e32 v65, v64
	v_mov_b32_e32 v66, v64
	v_mov_b32_e32 v67, v64
	v_mov_b32_e32 v68, v64
	v_mov_b32_e32 v69, v64
	v_mov_b32_e32 v70, v64
	v_mov_b32_e32 v71, v64
	v_mov_b32_e32 v72, v64
	v_mov_b32_e32 v73, v64
	v_mov_b32_e32 v74, v64
	v_mov_b32_e32 v75, v64
	v_mov_b32_e32 v76, v64
	v_mov_b32_e32 v77, v64
	v_mov_b32_e32 v78, v64
	v_mov_b32_e32 v79, v64
	v_mov_b64_e32 v[110:111], v[78:79]
	v_mov_b64_e32 v[108:109], v[76:77]
	v_mfma_f32_32x32x16_bf16 v[80:95], v[16:19], v[130:133], v[64:79]
	ds_read_b128 v[16:19], v180 offset:45568
	v_mov_b64_e32 v[106:107], v[74:75]
	v_mov_b64_e32 v[104:105], v[72:73]
	v_mov_b64_e32 v[102:103], v[70:71]
	v_mov_b64_e32 v[100:101], v[68:69]
	v_mov_b64_e32 v[98:99], v[66:67]
	v_mov_b64_e32 v[96:97], v[64:65]
	ds_read_b128 v[24:27], v180 offset:45600
	v_mfma_f32_32x32x16_bf16 v[80:95], v[20:23], v[134:137], v[80:95]
	v_sub_f32_e32 v28, v3, v159
	v_sub_f32_e32 v4, v4, v159
	v_sub_f32_e32 v5, v5, v159
	v_sub_f32_e32 v6, v6, v159
	v_exp_f32_e32 v202, v4
	v_exp_f32_e32 v203, v5
	v_exp_f32_e32 v65, v6
	s_waitcnt lgkmcnt(1)
	v_mfma_f32_32x32x16_bf16 v[96:111], v[16:19], v[130:133], v[96:111]
	ds_read_b128 v[16:19], v180 offset:36928
	v_exp_f32_e32 v201, v28
	v_sub_f32_e32 v66, v8, v159
	v_sub_f32_e32 v67, v9, v159
	v_sub_f32_e32 v68, v10, v159
	v_sub_f32_e32 v69, v11, v159
	v_exp_f32_e32 v190, v66
	s_waitcnt lgkmcnt(1)
	v_mfma_f32_32x32x16_bf16 v[96:111], v[24:27], v[134:137], v[96:111]
	ds_read_b128 v[20:23], v180 offset:45632
	ds_read_b128 v[24:27], v180 offset:36960
	v_exp_f32_e32 v191, v67
	v_exp_f32_e32 v192, v68
	v_exp_f32_e32 v193, v69
	v_sub_f32_e32 v12, v12, v159
	v_sub_f32_e32 v13, v13, v159
	v_sub_f32_e32 v70, v14, v159
	s_waitcnt lgkmcnt(2)
	v_mfma_f32_32x32x16_bf16 v[80:95], v[16:19], v[138:141], v[80:95]
	v_mul_u32_u24_e32 v16, 0x90, v36
	v_add3_u32 v188, 0, v16, v164
	v_sub_f32_e32 v17, v0, v159
	v_sub_f32_e32 v18, v1, v159
	v_sub_f32_e32 v19, v2, v159
	ds_read_b128 v[0:3], v180 offset:45664
	v_add_u32_e32 v185, 0x4000, v188
	s_waitcnt lgkmcnt(2)
	v_mfma_f32_32x32x16_bf16 v[96:111], v[20:23], v[138:141], v[96:111]
	v_sub_f32_e32 v20, v7, v159
	ds_read2_b64 v[4:7], v185 offset0:128 offset1:130
	v_add_u32_e32 v187, 0x5000, v188
	v_exp_f32_e32 v198, v17
	v_exp_f32_e32 v199, v18
	v_exp_f32_e32 v200, v19
	ds_read2_b64 v[16:19], v187 offset0:192 offset1:194
	v_exp_f32_e32 v79, v20
	s_waitcnt lgkmcnt(2)
	v_mfma_f32_32x32x16_bf16 v[96:111], v[0:3], v[142:145], v[96:111]
	v_cvt_pk_bf16_f32 v0, v198, v199
	v_cvt_pk_bf16_f32 v1, v200, v201
	v_cvt_pk_bf16_f32 v2, v202, v203
	v_cvt_pk_bf16_f32 v3, v65, v79
	v_add_u32_e32 v184, 0x6800, v188
	ds_read2_b64 v[66:69], v185 offset0:132 offset1:134
	v_add_u32_e32 v186, 0x7800, v188
	s_waitcnt lgkmcnt(2)
	v_mfma_f32_32x32x16_bf16 v[48:63], v[4:7], v[0:3], 0
	ds_read2_b64 v[4:7], v184 offset1:2
	ds_read2_b64 v[74:77], v187 offset0:196 offset1:198
	ds_read2_b64 v[8:11], v186 offset0:64 offset1:66
	v_sub_f32_e32 v71, v15, v159
	v_exp_f32_e32 v194, v12
	v_exp_f32_e32 v195, v13
	v_exp_f32_e32 v196, v70
	s_waitcnt lgkmcnt(4)
	v_mfma_f32_32x32x16_bf16 v[32:47], v[16:19], v[0:3], 0
	v_exp_f32_e32 v197, v71
	v_cvt_pk_bf16_f32 v70, v190, v191
	v_cvt_pk_bf16_f32 v71, v192, v193
	v_cvt_pk_bf16_f32 v72, v194, v195
	v_cvt_pk_bf16_f32 v73, v196, v197
	v_sub_f32_e32 v78, v112, v159
	v_sub_f32_e32 v112, v113, v159
	s_waitcnt lgkmcnt(3)
	v_mfma_f32_32x32x16_bf16 v[48:63], v[66:69], v[70:73], v[48:63]
	ds_read2_b64 v[66:69], v184 offset0:4 offset1:6
	v_sub_f32_e32 v113, v114, v159
	v_sub_f32_e32 v114, v115, v159
	v_sub_f32_e32 v115, v116, v159
	v_sub_f32_e32 v160, v117, v159
	v_sub_f32_e32 v161, v118, v159
	v_sub_f32_e32 v189, v119, v159
	v_mfma_f32_32x32x16_bf16 v[80:95], v[24:27], v[142:145], v[80:95]
	v_exp_f32_e32 v117, v112
	v_exp_f32_e32 v118, v113
	v_exp_f32_e32 v119, v114
	v_exp_f32_e32 v214, v115
	ds_read2_b64 v[112:115], v185 offset0:136 offset1:138
	v_exp_f32_e32 v116, v78
	v_exp_f32_e32 v215, v160
	s_waitcnt lgkmcnt(4)
	v_mfma_f32_32x32x16_bf16 v[16:31], v[4:7], v[0:3], 0
	v_exp_f32_e32 v204, v161
	v_exp_f32_e32 v205, v189
	v_cvt_pk_bf16_f32 v216, v116, v117
	v_cvt_pk_bf16_f32 v217, v118, v119
	v_cvt_pk_bf16_f32 v218, v214, v215
	v_cvt_pk_bf16_f32 v219, v204, v205
	v_sub_f32_e32 v78, v120, v159
	s_waitcnt lgkmcnt(3)
	v_mfma_f32_32x32x16_bf16 v[32:47], v[74:77], v[70:73], v[32:47]
	ds_read2_b64 v[74:77], v186 offset0:68 offset1:70
	v_sub_f32_e32 v124, v124, v159
	v_sub_f32_e32 v160, v126, v159
	v_exp_f32_e32 v210, v124
	v_exp_f32_e32 v206, v78
	v_exp_f32_e32 v212, v160
	s_waitcnt lgkmcnt(3)
	v_mfma_f32_32x32x16_bf16 v[0:15], v[8:11], v[0:3], 0
	s_waitcnt lgkmcnt(2)
	v_mfma_f32_32x32x16_bf16 v[16:31], v[66:69], v[70:73], v[16:31]
	v_lshl_add_u64 v[66:67], s[70:71], 0, v[150:151]
	v_lshl_add_u64 v[68:69], s[70:71], 0, v[154:155]
	v_lshl_add_u64 v[66:67], v[66:67], 0, v[152:153]
	s_waitcnt lgkmcnt(0)
	v_mfma_f32_32x32x16_bf16 v[0:15], v[74:77], v[70:73], v[0:15]
	v_lshl_add_u64 v[70:71], v[68:69], 0, v[156:157]
	global_load_dwordx4 v[66:69], v[66:67], off
	s_nop 0
	global_load_dwordx4 v[70:73], v[70:71], off
	ds_read2_b64 v[150:153], v187 offset0:200 offset1:202
	v_mfma_f32_32x32x16_bf16 v[48:63], v[112:115], v[216:219], v[48:63]
	global_load_dwordx4 v[74:77], v[172:173], off offset:256
	global_load_dwordx4 v[112:115], v[174:175], off offset:256
	ds_read2_b64 v[154:157], v184 offset0:8 offset1:10
	s_waitcnt lgkmcnt(1)
	v_mfma_f32_32x32x16_bf16 v[32:47], v[150:153], v[216:219], v[32:47]
	v_sub_f32_e32 v150, v121, v159
	v_sub_f32_e32 v151, v122, v159
	v_sub_f32_e32 v152, v123, v159
	ds_read2_b64 v[120:123], v186 offset0:72 offset1:74
	v_sub_f32_e32 v153, v125, v159
	v_exp_f32_e32 v207, v150
	v_exp_f32_e32 v208, v151
	s_waitcnt lgkmcnt(1)
	v_mfma_f32_32x32x16_bf16 v[16:31], v[154:157], v[216:219], v[16:31]
	v_sub_f32_e32 v154, v127, v159
	ds_read2_b64 v[124:127], v185 offset0:140 offset1:142
	v_exp_f32_e32 v209, v152
	v_exp_f32_e32 v211, v153
	v_exp_f32_e32 v213, v154
	s_waitcnt lgkmcnt(1)
	v_mfma_f32_32x32x16_bf16 v[0:15], v[120:123], v[216:219], v[0:15]
	v_cvt_pk_bf16_f32 v120, v206, v207
	v_cvt_pk_bf16_f32 v121, v208, v209
	v_cvt_pk_bf16_f32 v122, v210, v211
	v_cvt_pk_bf16_f32 v123, v212, v213
	s_waitcnt lgkmcnt(0)
	s_nop 0
	v_mfma_f32_32x32x16_bf16 v[48:63], v[124:127], v[120:123], v[48:63]
	ds_read2_b64 v[124:127], v187 offset0:204 offset1:206
	s_waitcnt lgkmcnt(0)
	v_mfma_f32_32x32x16_bf16 v[32:47], v[124:127], v[120:123], v[32:47]
	ds_read2_b64 v[124:127], v184 offset0:12 offset1:14
	s_waitcnt lgkmcnt(0)
	v_mfma_f32_32x32x16_bf16 v[16:31], v[124:127], v[120:123], v[16:31]
	ds_read2_b64 v[124:127], v186 offset0:76 offset1:78
	s_nop 15
	s_nop 7
	s_nop 0
	v_max3_f32 v78, v80, v81, v96
	s_nop 0
	v_max3_f32 v78, v78, v97, v82
	s_nop 0
	v_max3_f32 v78, v78, v98, v98
	s_waitcnt lgkmcnt(0)
	v_mfma_f32_32x32x16_bf16 v[0:15], v[124:127], v[120:123], v[0:15]
	v_max3_f32 v78, v78, v83, v99
	s_nop 0
	v_max3_f32 v78, v78, v84, v100
	s_nop 0
	v_max3_f32 v78, v78, v85, v101
	s_nop 0
	v_max3_f32 v78, v78, v86, v102
	s_nop 0
	v_max3_f32 v78, v78, v87, v103
	s_nop 0
	v_max3_f32 v78, v78, v88, v104
	s_nop 0
	v_max3_f32 v78, v78, v89, v105
	s_nop 0
	v_max3_f32 v78, v78, v90, v106
	s_nop 0
	v_max3_f32 v78, v78, v91, v107
	s_nop 0
	v_max3_f32 v78, v78, v92, v108
	s_nop 0
	v_max3_f32 v78, v78, v93, v109
	s_nop 0
	v_max3_f32 v78, v78, v94, v110
	s_nop 0
	v_max3_f32 v78, v78, v95, v111
	ds_bpermute_b32 v150, v163, v78
	v_max_f32_e32 v78, v78, v78
	s_waitcnt lgkmcnt(0)
	v_max_f32_e32 v120, v150, v150
	v_max_f32_e32 v78, v78, v120
	v_cmp_lt_f32_e32 vcc, 0x41000000, v78
	s_cbranch_vccz .LBB0_1185
	v_max_f32_e32 v64, v78, v78
	v_max_f32_e32 v120, 0, v64
	v_exp_f32_e64 v78, -v120
	v_add_f32_e32 v181, v181, v120
	v_xor_b32_e32 v64, 0x80000000, v181
	v_pk_add_f32 v[80:81], v[80:81], v[120:121] op_sel_hi:[1,0] neg_lo:[0,1] neg_hi:[0,1]
	v_pk_add_f32 v[96:97], v[96:97], v[120:121] op_sel_hi:[1,0] neg_lo:[0,1] neg_hi:[0,1]
	v_pk_add_f32 v[82:83], v[82:83], v[120:121] op_sel_hi:[1,0] neg_lo:[0,1] neg_hi:[0,1]
	v_pk_add_f32 v[98:99], v[98:99], v[120:121] op_sel_hi:[1,0] neg_lo:[0,1] neg_hi:[0,1]
	v_pk_add_f32 v[84:85], v[84:85], v[120:121] op_sel_hi:[1,0] neg_lo:[0,1] neg_hi:[0,1]
	v_pk_add_f32 v[100:101], v[100:101], v[120:121] op_sel_hi:[1,0] neg_lo:[0,1] neg_hi:[0,1]
	v_pk_add_f32 v[86:87], v[86:87], v[120:121] op_sel_hi:[1,0] neg_lo:[0,1] neg_hi:[0,1]
	v_pk_add_f32 v[102:103], v[102:103], v[120:121] op_sel_hi:[1,0] neg_lo:[0,1] neg_hi:[0,1]
	v_pk_add_f32 v[88:89], v[88:89], v[120:121] op_sel_hi:[1,0] neg_lo:[0,1] neg_hi:[0,1]
	v_pk_add_f32 v[104:105], v[104:105], v[120:121] op_sel_hi:[1,0] neg_lo:[0,1] neg_hi:[0,1]
	v_pk_add_f32 v[90:91], v[90:91], v[120:121] op_sel_hi:[1,0] neg_lo:[0,1] neg_hi:[0,1]
	v_pk_add_f32 v[106:107], v[106:107], v[120:121] op_sel_hi:[1,0] neg_lo:[0,1] neg_hi:[0,1]
	v_pk_add_f32 v[92:93], v[92:93], v[120:121] op_sel_hi:[1,0] neg_lo:[0,1] neg_hi:[0,1]
	v_pk_add_f32 v[108:109], v[108:109], v[120:121] op_sel_hi:[1,0] neg_lo:[0,1] neg_hi:[0,1]
	v_pk_add_f32 v[94:95], v[94:95], v[120:121] op_sel_hi:[1,0] neg_lo:[0,1] neg_hi:[0,1]
	v_pk_add_f32 v[110:111], v[110:111], v[120:121] op_sel_hi:[1,0] neg_lo:[0,1] neg_hi:[0,1]
	v_cmp_neq_f32_e32 vcc, 1.0, v78
	s_cbranch_vccz .LBB0_1120

.LBB0_1121:
	s_mov_b32 s70, s66
	s_mov_b32 s66, s71
	s_mul_i32 s71, s71, 0x9000
	v_add_u32_e32 v169, s71, v180
	ds_read_b128 v[96:99], v169
	ds_read_b128 v[170:173], v169 offset:8704
	s_mul_i32 s71, s70, 0x9000
	s_waitcnt lgkmcnt(1)
	v_mfma_f32_32x32x16_bf16 v[80:95], v[96:99], v[130:133], v[64:79]
	v_mov_b64_e32 v[110:111], v[78:79]
	v_mov_b64_e32 v[108:109], v[76:77]
	v_mov_b64_e32 v[106:107], v[74:75]
	v_mov_b64_e32 v[104:105], v[72:73]
	v_mov_b64_e32 v[102:103], v[70:71]
	v_mov_b64_e32 v[100:101], v[68:69]
	v_mov_b64_e32 v[98:99], v[66:67]
	v_mov_b64_e32 v[96:97], v[64:65]
	s_waitcnt lgkmcnt(0)
	s_nop 0
	v_mfma_f32_32x32x16_bf16 v[96:111], v[170:173], v[130:133], v[96:111]
	ds_read_b128 v[170:173], v169 offset:32
	s_waitcnt lgkmcnt(0)
	v_mfma_f32_32x32x16_bf16 v[80:95], v[170:173], v[134:137], v[80:95]
	ds_read_b128 v[170:173], v169 offset:8736
	s_waitcnt lgkmcnt(0)
	v_mfma_f32_32x32x16_bf16 v[96:111], v[170:173], v[134:137], v[96:111]
	ds_read_b128 v[170:173], v169 offset:64
	s_waitcnt lgkmcnt(0)
	v_mfma_f32_32x32x16_bf16 v[80:95], v[170:173], v[138:141], v[80:95]
	ds_read_b128 v[170:173], v169 offset:8768
	s_waitcnt lgkmcnt(0)
	v_mfma_f32_32x32x16_bf16 v[96:111], v[170:173], v[138:141], v[96:111]
	ds_read_b128 v[170:173], v169 offset:96
	s_waitcnt lgkmcnt(0)
	v_mfma_f32_32x32x16_bf16 v[80:95], v[170:173], v[142:145], v[80:95]
	ds_read_b128 v[170:173], v169 offset:8800
	v_add_u32_e32 v169, s71, v188
	v_add_u32_e32 v174, 0x4000, v169
	v_add_u32_e32 v175, 0x5000, v169
	v_add_u32_e32 v190, 0x6800, v169
	v_add_u32_e32 v169, 0x7800, v169
	s_waitcnt lgkmcnt(0)
	v_mfma_f32_32x32x16_bf16 v[96:111], v[170:173], v[142:145], v[96:111]
	ds_read2_b64 v[170:173], v174 offset0:128 offset1:130
	s_waitcnt lgkmcnt(0)
	v_mfma_f32_32x32x16_bf16 v[48:63], v[170:173], v[158:161], v[48:63]
	ds_read2_b64 v[170:173], v175 offset0:192 offset1:194
	s_waitcnt lgkmcnt(0)
	v_mfma_f32_32x32x16_bf16 v[32:47], v[170:173], v[158:161], v[32:47]
	ds_read2_b64 v[170:173], v190 offset1:2
	s_waitcnt lgkmcnt(0)
	v_mfma_f32_32x32x16_bf16 v[16:31], v[170:173], v[158:161], v[16:31]
	ds_read2_b64 v[170:173], v169 offset0:64 offset1:66
	s_waitcnt lgkmcnt(0)
	v_mfma_f32_32x32x16_bf16 v[0:15], v[170:173], v[158:161], v[0:15]
	ds_read2_b64 v[158:161], v174 offset0:132 offset1:134
	s_waitcnt lgkmcnt(0)
	v_mfma_f32_32x32x16_bf16 v[48:63], v[158:161], v[154:157], v[48:63]
	ds_read2_b64 v[158:161], v175 offset0:196 offset1:198
	s_waitcnt lgkmcnt(0)
	v_mfma_f32_32x32x16_bf16 v[32:47], v[158:161], v[154:157], v[32:47]
	ds_read2_b64 v[158:161], v190 offset0:4 offset1:6
	s_waitcnt lgkmcnt(0)
	v_mfma_f32_32x32x16_bf16 v[16:31], v[158:161], v[154:157], v[16:31]
	ds_read2_b64 v[158:161], v169 offset0:68 offset1:70
	s_waitcnt lgkmcnt(0)
	v_mfma_f32_32x32x16_bf16 v[0:15], v[158:161], v[154:157], v[0:15]
	ds_read2_b64 v[154:157], v174 offset0:136 offset1:138
	s_waitcnt lgkmcnt(0)
	v_mfma_f32_32x32x16_bf16 v[48:63], v[154:157], v[150:153], v[48:63]
	ds_read2_b64 v[154:157], v175 offset0:200 offset1:202
	s_waitcnt lgkmcnt(0)
	v_mfma_f32_32x32x16_bf16 v[32:47], v[154:157], v[150:153], v[32:47]
	ds_read2_b64 v[154:157], v190 offset0:8 offset1:10
	s_waitcnt lgkmcnt(0)
	v_mfma_f32_32x32x16_bf16 v[16:31], v[154:157], v[150:153], v[16:31]
	ds_read2_b64 v[154:157], v169 offset0:72 offset1:74
	s_waitcnt lgkmcnt(0)
	v_mfma_f32_32x32x16_bf16 v[0:15], v[154:157], v[150:153], v[0:15]
	ds_read2_b64 v[150:153], v174 offset0:140 offset1:142
	ds_read2_b64 v[154:157], v175 offset0:204 offset1:206
	ds_read2_b64 v[158:161], v190 offset0:12 offset1:14
	ds_read2_b64 v[170:173], v169 offset0:76 offset1:78
	s_nop 15
	s_nop 7
	s_waitcnt lgkmcnt(3)
	v_mfma_f32_32x32x16_bf16 v[48:63], v[150:153], v[146:149], v[48:63]
	v_max3_f32 v150, v80, v81, v96
	s_nop 0
	v_max3_f32 v150, v150, v97, v82
	s_nop 0
	v_max3_f32 v150, v150, v98, v98
	s_nop 0
	v_max3_f32 v150, v150, v83, v99
	s_waitcnt lgkmcnt(2)
	v_mfma_f32_32x32x16_bf16 v[32:47], v[154:157], v[146:149], v[32:47]
	v_max3_f32 v150, v150, v84, v100
	s_nop 0
	v_max3_f32 v150, v150, v85, v101
	s_nop 0
	v_max3_f32 v150, v150, v86, v102
	s_nop 0
	v_max3_f32 v150, v150, v87, v103
	s_waitcnt lgkmcnt(1)
	v_mfma_f32_32x32x16_bf16 v[16:31], v[158:161], v[146:149], v[16:31]
	v_max3_f32 v150, v150, v88, v104
	s_nop 0
	v_max3_f32 v150, v150, v89, v105
	s_nop 0
	v_max3_f32 v150, v150, v90, v106
	s_nop 0
	v_max3_f32 v150, v150, v91, v107
	s_waitcnt lgkmcnt(0)
	v_mfma_f32_32x32x16_bf16 v[0:15], v[170:173], v[146:149], v[0:15]
	v_max3_f32 v150, v150, v92, v108
	s_nop 0
	v_max3_f32 v150, v150, v93, v109
	s_nop 0
	v_max3_f32 v150, v150, v94, v110
	s_nop 0
	v_max3_f32 v150, v150, v95, v111
	ds_bpermute_b32 v151, v163, v150
	v_max_f32_e32 v150, v150, v150
	s_waitcnt lgkmcnt(0)
	v_max_f32_e32 v151, v151, v151
	v_max_f32_e32 v150, v150, v151
	v_cmp_lt_f32_e32 vcc, 0x41000000, v150
	s_cbranch_vccz .LBB0_1128
	v_max_f32_e32 v64, v150, v150
	v_max_f32_e32 v66, 0, v64
	v_exp_f32_e64 v146, -v66
	v_add_f32_e32 v181, v181, v66
	v_xor_b32_e32 v64, 0x80000000, v181
	v_pk_add_f32 v[80:81], v[80:81], v[66:67] op_sel_hi:[1,0] neg_lo:[0,1] neg_hi:[0,1]
	v_pk_add_f32 v[96:97], v[96:97], v[66:67] op_sel_hi:[1,0] neg_lo:[0,1] neg_hi:[0,1]
	v_pk_add_f32 v[82:83], v[82:83], v[66:67] op_sel_hi:[1,0] neg_lo:[0,1] neg_hi:[0,1]
	v_pk_add_f32 v[98:99], v[98:99], v[66:67] op_sel_hi:[1,0] neg_lo:[0,1] neg_hi:[0,1]
	v_pk_add_f32 v[84:85], v[84:85], v[66:67] op_sel_hi:[1,0] neg_lo:[0,1] neg_hi:[0,1]
	v_pk_add_f32 v[100:101], v[100:101], v[66:67] op_sel_hi:[1,0] neg_lo:[0,1] neg_hi:[0,1]
	v_pk_add_f32 v[86:87], v[86:87], v[66:67] op_sel_hi:[1,0] neg_lo:[0,1] neg_hi:[0,1]
	v_pk_add_f32 v[102:103], v[102:103], v[66:67] op_sel_hi:[1,0] neg_lo:[0,1] neg_hi:[0,1]
	v_pk_add_f32 v[88:89], v[88:89], v[66:67] op_sel_hi:[1,0] neg_lo:[0,1] neg_hi:[0,1]
	v_pk_add_f32 v[104:105], v[104:105], v[66:67] op_sel_hi:[1,0] neg_lo:[0,1] neg_hi:[0,1]
	v_pk_add_f32 v[90:91], v[90:91], v[66:67] op_sel_hi:[1,0] neg_lo:[0,1] neg_hi:[0,1]
	v_pk_add_f32 v[106:107], v[106:107], v[66:67] op_sel_hi:[1,0] neg_lo:[0,1] neg_hi:[0,1]
	v_pk_add_f32 v[92:93], v[92:93], v[66:67] op_sel_hi:[1,0] neg_lo:[0,1] neg_hi:[0,1]
	v_pk_add_f32 v[108:109], v[108:109], v[66:67] op_sel_hi:[1,0] neg_lo:[0,1] neg_hi:[0,1]
	v_pk_add_f32 v[94:95], v[94:95], v[66:67] op_sel_hi:[1,0] neg_lo:[0,1] neg_hi:[0,1]
	v_pk_add_f32 v[110:111], v[110:111], v[66:67] op_sel_hi:[1,0] neg_lo:[0,1] neg_hi:[0,1]
	v_mov_b32_e32 v65, v64
	v_mov_b32_e32 v66, v64
	v_mov_b32_e32 v67, v64
	v_mov_b32_e32 v68, v64
	v_mov_b32_e32 v69, v64
	v_mov_b32_e32 v70, v64
	v_mov_b32_e32 v71, v64
	v_mov_b32_e32 v72, v64
	v_mov_b32_e32 v73, v64
	v_mov_b32_e32 v74, v64
	v_mov_b32_e32 v75, v64
	v_mov_b32_e32 v76, v64
	v_mov_b32_e32 v77, v64
	v_mov_b32_e32 v78, v64
	v_mov_b32_e32 v79, v64
	v_cmp_neq_f32_e32 vcc, 1.0, v146
	s_cbranch_vccz .LBB0_1124

.LBB0_1139:
	s_lshr_b32 s19, s62, 3
	s_lshl_b32 s20, s62, 7
	s_lshl_b32 s18, s19, 8
	s_and_b32 s20, s20, 0x80
	s_or_b32 s18, s18, s20
	s_bfe_u32 s24, s62, 0x10002
	s_lshl_b32 s20, s18, 10
	s_add_u32 s20, s47, s20
	s_addc_u32 s21, s48, 0
	s_lshl_b32 s23, s62, 6
	s_lshl_b32 s22, s24, 8
	s_and_b32 s23, s23, 0x80
	s_or_b32 s26, s22, s23
	s_or_b32 s27, s26, 64
	s_lshl_b32 s19, s19, 16
	s_add_u32 s22, s49, s19
	s_addc_u32 s23, s50, 0
	s_lshl_b32 s25, s24, 7
	s_add_u32 s22, s22, s25
	v_mov_b32_e32 v14, v244
	s_addc_u32 s23, s23, 0
	s_add_u32 s19, s51, s19
	v_ashrrev_i32_e32 v0, 31, v14
	v_lshrrev_b32_e32 v0, 29, v0
	s_addc_u32 s25, s54, 0
	s_lshl_b32 s24, s24, 15
	v_add_u32_e32 v0, v14, v0
	s_add_u32 s24, s19, s24
	v_readfirstlane_b32 s19, v14
	v_ashrrev_i32_e32 v10, 3, v0
	v_and_b32_e32 v0, -8, v0
	s_addc_u32 s25, s25, 0
	s_lshr_b32 s63, s19, 1
	v_sub_u32_e32 v17, v14, v0
	v_ashrrev_i32_e32 v11, 31, v10
	v_and_b32_e32 v16, 31, v14
	s_and_b32 s63, s63, 0x60
	v_lshlrev_b64 v[0:1], 8, v[10:11]
	v_lshlrev_b32_e32 v2, 3, v17
	v_ashrrev_i32_e32 v12, 3, v14
	s_waitcnt vmcnt(9)
	v_or_b32_e32 v98, s63, v16
	v_lshl_add_u64 v[0:1], s[22:23], 0, v[0:1]
	v_ashrrev_i32_e32 v3, 31, v2
	v_ashrrev_i32_e32 v13, 31, v12
	v_lshlrev_b32_e32 v128, 10, v98
	v_lshl_add_u64 v[96:97], v[2:3], 1, v[0:1]
	v_lshlrev_b64 v[0:1], 9, v[12:13]
	v_lshlrev_b32_e32 v2, 4, v14
	v_lshl_add_u64 v[8:9], s[20:21], 0, v[128:129]
	v_lshl_add_u64 v[0:1], s[24:25], 0, v[0:1]
	v_and_b32_e32 v128, 0x70, v2
	s_waitcnt vmcnt(8)
	v_lshl_add_u64 v[100:101], v[0:1], 0, v[128:129]
	global_load_dwordx4 v[0:3], v[96:97], off
	global_load_dwordx4 v[4:7], v[100:101], off
	s_cmpk_lt_u32 s19, 0x100
	s_cselect_b32 s19, s26, s27
	s_waitcnt vmcnt(3)
	v_bfe_u32 v120, v14, 5, 1
	s_lshl_b32 s68, s19, 1
	v_lshlrev_b32_e32 v14, 4, v120
	v_lshl_add_u64 v[8:9], v[8:9], 0, s[68:69]
	v_mov_b32_e32 v15, v129
	v_lshl_add_u64 v[8:9], v[8:9], 0, v[14:15]
	global_load_dwordx4 v[80:83], v[8:9], off
	global_load_dwordx4 v[84:87], v[8:9], off offset:32
	global_load_dwordx4 v[88:91], v[8:9], off offset:64
	global_load_dwordx4 v[92:95], v[8:9], off offset:96
	s_movk_i32 s19, 0x90
	v_mad_u32_u24 v26, v16, s19, 0
	v_mul_lo_u32 v123, v10, s19
	s_waitcnt vmcnt(6)
	v_lshlrev_b32_e32 v124, 4, v17
	v_mul_lo_u32 v121, v12, s19
	v_add_u32_e32 v122, v26, v14
	v_add3_u32 v24, 0, v123, v124
	v_add3_u32 v25, 0, v121, v128
	s_movk_i32 s19, 0x4000
	v_and_b32_e32 v32, 64, v248
	v_xor_b32_e32 v27, 32, v248
	v_add_u32_e32 v32, 64, v32
	v_lshl_add_u32 v127, v120, 3, v26
	v_add_u32_e32 v126, 0x4000, v127
	v_add_u32_e32 v131, 0x5000, v127
	s_waitcnt vmcnt(5)
	ds_write_b128 v24, v[0:3]
	s_waitcnt vmcnt(4)
	ds_write_b128 v25, v[4:7] offset:17408
	s_waitcnt lgkmcnt(0)
	s_barrier
	ds_read_b128 v[0:3], v122
	ds_read_b128 v[16:19], v122 offset:32
	s_waitcnt vmcnt(3) lgkmcnt(1)
	v_mfma_f32_32x32x16_bf16 v[0:15], v[0:3], v[80:83], 0
	ds_read_b128 v[20:23], v122 offset:4608
	ds_read_b128 v[28:31], v122 offset:4640
	s_waitcnt lgkmcnt(1)
	v_mfma_f32_32x32x16_bf16 v[48:63], v[20:23], v[80:83], 0
	s_waitcnt vmcnt(2)
	v_mfma_f32_32x32x16_bf16 v[0:15], v[16:19], v[84:87], v[0:15]
	ds_read_b128 v[16:19], v122 offset:64
	ds_read_b128 v[20:23], v122 offset:96
	s_waitcnt lgkmcnt(2)
	v_mfma_f32_32x32x16_bf16 v[48:63], v[28:31], v[84:87], v[48:63]
	s_waitcnt vmcnt(1) lgkmcnt(1)
	v_mfma_f32_32x32x16_bf16 v[0:15], v[16:19], v[88:91], v[0:15]
	ds_read_b128 v[16:19], v122 offset:4672
	ds_read_b128 v[28:31], v122 offset:4704
	s_waitcnt lgkmcnt(1)
	v_mfma_f32_32x32x16_bf16 v[48:63], v[16:19], v[88:91], v[48:63]
	v_add_co_u32_e32 v16, vcc, s19, v96
	s_mov_b32 s19, 0x8000
	s_nop 0
	v_addc_co_u32_e32 v17, vcc, 0, v97, vcc
	global_load_dwordx4 v[16:19], v[16:17], off
	v_cmp_lt_i32_e32 vcc, v27, v32
	s_waitcnt vmcnt(1)
	v_mfma_f32_32x32x16_bf16 v[0:15], v[20:23], v[92:95], v[0:15]
	global_load_dwordx4 v[20:23], v[100:101], off offset:128
	v_cndmask_b32_e32 v27, v248, v27, vcc
	v_lshlrev_b32_e32 v125, 2, v27
	s_waitcnt lgkmcnt(0)
	v_mfma_f32_32x32x16_bf16 v[48:63], v[28:31], v[92:95], v[48:63]
	s_nop 15
	s_nop 7
	s_waitcnt vmcnt(1)
	ds_write_b128 v24, v[16:19] offset:36864
	s_waitcnt vmcnt(0)
	ds_write_b128 v25, v[20:23] offset:54272
	v_max3_f32 v27, v0, v1, v48
	s_waitcnt lgkmcnt(0)
	v_max3_f32 v27, v27, v49, v2
	s_barrier
	v_max3_f32 v27, v27, v50, v50
	s_nop 0
	v_max3_f32 v27, v27, v3, v51
	ds_read_b128 v[16:19], v122 offset:36864
	v_max3_f32 v27, v27, v4, v52
	s_nop 0
	v_max3_f32 v27, v27, v5, v53
	s_nop 0
	v_max3_f32 v27, v27, v6, v54
	s_nop 0
	v_max3_f32 v27, v27, v7, v55
	s_nop 0
	v_max3_f32 v27, v27, v8, v56
	s_nop 0
	v_max3_f32 v27, v27, v9, v57
	s_nop 0
	v_max3_f32 v27, v27, v10, v58
	s_nop 0
	v_max3_f32 v27, v27, v11, v59
	s_nop 0
	v_max3_f32 v27, v27, v12, v60
	s_nop 0
	v_max3_f32 v27, v27, v13, v61
	s_nop 0
	v_max3_f32 v27, v27, v14, v62
	s_nop 0
	v_max3_f32 v27, v27, v15, v63
	ds_bpermute_b32 v28, v125, v27
	v_max_f32_e32 v26, v27, v27
	s_waitcnt lgkmcnt(0)
	v_max_f32_e32 v27, v28, v28
	v_max_f32_e32 v104, v26, v27
	v_add_f32_e32 v130, 0, v104
	v_xor_b32_e32 v32, 0x80000000, v130
	ds_read_b128 v[20:23], v122 offset:41472
	ds_read_b128 v[24:27], v122 offset:36896
	v_mov_b32_e32 v33, v32
	v_mov_b32_e32 v34, v32
	v_mov_b32_e32 v35, v32
	v_mov_b32_e32 v36, v32
	v_mov_b32_e32 v37, v32
	v_mov_b32_e32 v38, v32
	v_mov_b32_e32 v39, v32
	v_mov_b32_e32 v40, v32
	v_mov_b32_e32 v41, v32
	v_mov_b32_e32 v42, v32
	v_mov_b32_e32 v43, v32
	v_mov_b32_e32 v44, v32
	v_mov_b32_e32 v45, v32
	v_mov_b32_e32 v46, v32
	v_mov_b32_e32 v47, v32
	v_sub_f32_e32 v105, v48, v104
	v_sub_f32_e32 v118, v49, v104
	v_mfma_f32_32x32x16_bf16 v[64:79], v[16:19], v[80:83], v[32:47]
	v_mov_b64_e32 v[48:49], v[46:47]
	ds_read_b128 v[16:19], v122 offset:41504
	v_sub_f32_e32 v28, v0, v104
	v_sub_f32_e32 v29, v1, v104
	v_sub_f32_e32 v30, v2, v104
	s_nop 1
	v_mov_b64_e32 v[46:47], v[44:45]
	v_mov_b64_e32 v[44:45], v[42:43]
	v_mov_b64_e32 v[42:43], v[40:41]
	v_mov_b64_e32 v[40:41], v[38:39]
	v_mov_b64_e32 v[38:39], v[36:37]
	v_mov_b64_e32 v[36:37], v[34:35]
	v_mov_b64_e32 v[34:35], v[32:33]
	v_sub_f32_e32 v106, v8, v104
	v_sub_f32_e32 v107, v9, v104
	s_waitcnt lgkmcnt(2)
	v_mfma_f32_32x32x16_bf16 v[34:49], v[20:23], v[80:83], v[34:49]
	v_sub_f32_e32 v20, v3, v104
	ds_read_b128 v[0:3], v122 offset:36928
	v_sub_f32_e32 v108, v10, v104
	v_sub_f32_e32 v109, v11, v104
	v_sub_f32_e32 v21, v4, v104
	v_sub_f32_e32 v22, v5, v104
	v_sub_f32_e32 v23, v6, v104
	s_waitcnt lgkmcnt(1)
	v_mfma_f32_32x32x16_bf16 v[34:49], v[16:19], v[84:87], v[34:49]
	ds_read_b128 v[8:11], v122 offset:41536
	ds_read_b128 v[16:19], v122 offset:36960
	v_sub_f32_e32 v119, v50, v104
	v_sub_f32_e32 v132, v51, v104
	v_sub_f32_e32 v141, v52, v104
	v_sub_f32_e32 v144, v53, v104
	v_sub_f32_e32 v145, v54, v104
	v_sub_f32_e32 v146, v55, v104
	v_mfma_f32_32x32x16_bf16 v[64:79], v[24:27], v[84:87], v[64:79]
	v_sub_f32_e32 v24, v7, v104
	ds_read_b128 v[4:7], v122 offset:41568
	v_sub_f32_e32 v147, v56, v104
	v_sub_f32_e32 v148, v57, v104
	v_sub_f32_e32 v153, v59, v104
	v_sub_f32_e32 v154, v60, v104
	v_sub_f32_e32 v155, v61, v104
	s_waitcnt lgkmcnt(2)
	v_mfma_f32_32x32x16_bf16 v[34:49], v[8:11], v[88:91], v[34:49]
	ds_read2_b64 v[8:11], v126 offset0:128 offset1:130
	v_sub_f32_e32 v156, v62, v104
	v_exp_f32_e32 v103, v28
	v_exp_f32_e32 v102, v29
	v_exp_f32_e32 v99, v30
	v_exp_f32_e32 v62, v20
	v_exp_f32_e32 v61, v21
	s_waitcnt lgkmcnt(1)
	v_mfma_f32_32x32x16_bf16 v[34:49], v[4:7], v[92:95], v[34:49]
	v_add_co_u32_e32 v4, vcc, s19, v96
	v_exp_f32_e32 v59, v22
	s_nop 0
	v_addc_co_u32_e32 v5, vcc, 0, v97, vcc
	global_load_dwordx4 v[50:53], v[4:5], off
	global_load_dwordx4 v[54:57], v[100:101], off offset:256
	v_exp_f32_e32 v60, v23
	v_mfma_f32_32x32x16_bf16 v[64:79], v[0:3], v[88:91], v[64:79]
	v_exp_f32_e32 v33, v24
	v_cvt_pk_bf16_f32 v0, v103, v102
	v_cvt_pk_bf16_f32 v1, v99, v62
	v_cvt_pk_bf16_f32 v2, v61, v59
	v_cvt_pk_bf16_f32 v3, v60, v33
	ds_read2_b64 v[4:7], v131 offset0:192 offset1:194
	v_exp_f32_e32 v138, v106
	v_exp_f32_e32 v137, v107
	v_exp_f32_e32 v136, v108
	v_exp_f32_e32 v135, v109
	ds_read2_b64 v[106:109], v126 offset0:132 offset1:134
	v_mfma_f32_32x32x16_bf16 v[64:79], v[16:19], v[92:95], v[64:79]
	v_sub_f32_e32 v12, v12, v104
	v_sub_f32_e32 v13, v13, v104
	v_sub_f32_e32 v110, v14, v104
	v_sub_f32_e32 v111, v15, v104
	v_exp_f32_e32 v134, v12
	v_exp_f32_e32 v133, v13
	v_exp_f32_e32 v140, v110
	s_waitcnt lgkmcnt(2)
	v_mfma_f32_32x32x16_bf16 v[16:31], v[8:11], v[0:3], 0
	v_exp_f32_e32 v139, v111
	v_cvt_pk_bf16_f32 v110, v138, v137
	v_cvt_pk_bf16_f32 v111, v136, v135
	v_cvt_pk_bf16_f32 v112, v134, v133
	v_cvt_pk_bf16_f32 v113, v140, v139
	ds_read2_b64 v[114:117], v131 offset0:196 offset1:198
	v_exp_f32_e32 v152, v105
	s_waitcnt lgkmcnt(2)
	v_mfma_f32_32x32x16_bf16 v[0:15], v[4:7], v[0:3], 0
	v_exp_f32_e32 v151, v118
	v_exp_f32_e32 v150, v119
	v_exp_f32_e32 v143, v132
	v_exp_f32_e32 v142, v141
	v_exp_f32_e32 v141, v144
	v_exp_f32_e32 v145, v145
	v_exp_f32_e32 v144, v146
	s_waitcnt lgkmcnt(1)
	v_mfma_f32_32x32x16_bf16 v[16:31], v[106:109], v[110:113], v[16:31]
	ds_read2_b64 v[106:109], v126 offset0:136 offset1:138
	v_sub_f32_e32 v58, v58, v104
	v_exp_f32_e32 v149, v147
	v_exp_f32_e32 v148, v148
	v_exp_f32_e32 v147, v58
	v_exp_f32_e32 v146, v153
	v_exp_f32_e32 v155, v155
	s_waitcnt lgkmcnt(1)
	v_mfma_f32_32x32x16_bf16 v[0:15], v[114:117], v[110:113], v[0:15]
	v_cvt_pk_bf16_f32 v110, v152, v151
	v_cvt_pk_bf16_f32 v111, v150, v143
	v_cvt_pk_bf16_f32 v112, v142, v141
	v_cvt_pk_bf16_f32 v113, v145, v144
	ds_read2_b64 v[114:117], v131 offset0:200 offset1:202
	s_waitcnt lgkmcnt(1)
	v_mfma_f32_32x32x16_bf16 v[16:31], v[106:109], v[110:113], v[16:31]
	v_sub_f32_e32 v108, v63, v104
	ds_read2_b64 v[104:107], v126 offset0:140 offset1:142
	v_exp_f32_e32 v63, v154
	v_exp_f32_e32 v154, v156
	v_exp_f32_e32 v153, v108
	v_cvt_pk_bf16_f32 v108, v149, v148
	v_cvt_pk_bf16_f32 v109, v147, v146
	s_waitcnt lgkmcnt(1)
	v_mfma_f32_32x32x16_bf16 v[0:15], v[114:117], v[110:113], v[0:15]
	v_cvt_pk_bf16_f32 v110, v63, v155
	v_cvt_pk_bf16_f32 v111, v154, v153
	s_waitcnt lgkmcnt(0)
	s_nop 0
	v_mfma_f32_32x32x16_bf16 v[16:31], v[104:107], v[108:111], v[16:31]
	ds_read2_b64 v[104:107], v131 offset0:204 offset1:206
	s_nop 15
	s_nop 7
	s_nop 0
	v_max3_f32 v58, v64, v65, v34
	s_nop 0
	v_max3_f32 v58, v58, v35, v66
	s_nop 0
	v_max3_f32 v58, v58, v36, v36
	s_waitcnt lgkmcnt(0)
	v_mfma_f32_32x32x16_bf16 v[0:15], v[104:107], v[108:111], v[0:15]
	v_max3_f32 v58, v58, v67, v37
	s_nop 0
	v_max3_f32 v58, v58, v68, v38
	s_nop 0
	v_max3_f32 v58, v58, v69, v39
	s_nop 0
	v_max3_f32 v58, v58, v70, v40
	s_nop 0
	v_max3_f32 v58, v58, v71, v41
	s_nop 0
	v_max3_f32 v58, v58, v72, v42
	s_nop 0
	v_max3_f32 v58, v58, v73, v43
	s_nop 0
	v_max3_f32 v58, v58, v74, v44
	s_nop 0
	v_max3_f32 v58, v58, v75, v45
	s_nop 0
	v_max3_f32 v58, v58, v76, v46
	s_nop 0
	v_max3_f32 v58, v58, v77, v47
	s_nop 0
	v_max3_f32 v58, v58, v78, v48
	s_nop 0
	v_max3_f32 v58, v58, v79, v49
	ds_bpermute_b32 v112, v125, v58
	v_max_f32_e32 v58, v58, v58
	s_waitcnt lgkmcnt(0)
	v_max_f32_e32 v104, v112, v112
	v_max_f32_e32 v58, v58, v104
	v_cmp_lt_f32_e32 vcc, 0x41000000, v58
	s_cbranch_vccz .LBB0_1163
	v_max_f32_e32 v32, v58, v58
	v_max_f32_e32 v104, 0, v32
	v_exp_f32_e64 v58, -v104
	v_add_f32_e32 v130, v130, v104
	v_xor_b32_e32 v32, 0x80000000, v130
	v_pk_add_f32 v[64:65], v[64:65], v[104:105] op_sel_hi:[1,0] neg_lo:[0,1] neg_hi:[0,1]
	v_pk_add_f32 v[34:35], v[34:35], v[104:105] op_sel_hi:[1,0] neg_lo:[0,1] neg_hi:[0,1]
	v_pk_add_f32 v[66:67], v[66:67], v[104:105] op_sel_hi:[1,0] neg_lo:[0,1] neg_hi:[0,1]
	v_pk_add_f32 v[36:37], v[36:37], v[104:105] op_sel_hi:[1,0] neg_lo:[0,1] neg_hi:[0,1]
	v_pk_add_f32 v[68:69], v[68:69], v[104:105] op_sel_hi:[1,0] neg_lo:[0,1] neg_hi:[0,1]
	v_pk_add_f32 v[38:39], v[38:39], v[104:105] op_sel_hi:[1,0] neg_lo:[0,1] neg_hi:[0,1]
	v_pk_add_f32 v[70:71], v[70:71], v[104:105] op_sel_hi:[1,0] neg_lo:[0,1] neg_hi:[0,1]
	v_pk_add_f32 v[40:41], v[40:41], v[104:105] op_sel_hi:[1,0] neg_lo:[0,1] neg_hi:[0,1]
	v_pk_add_f32 v[72:73], v[72:73], v[104:105] op_sel_hi:[1,0] neg_lo:[0,1] neg_hi:[0,1]
	v_pk_add_f32 v[42:43], v[42:43], v[104:105] op_sel_hi:[1,0] neg_lo:[0,1] neg_hi:[0,1]
	v_pk_add_f32 v[74:75], v[74:75], v[104:105] op_sel_hi:[1,0] neg_lo:[0,1] neg_hi:[0,1]
	v_pk_add_f32 v[44:45], v[44:45], v[104:105] op_sel_hi:[1,0] neg_lo:[0,1] neg_hi:[0,1]
	v_pk_add_f32 v[76:77], v[76:77], v[104:105] op_sel_hi:[1,0] neg_lo:[0,1] neg_hi:[0,1]
	v_pk_add_f32 v[46:47], v[46:47], v[104:105] op_sel_hi:[1,0] neg_lo:[0,1] neg_hi:[0,1]
	v_pk_add_f32 v[78:79], v[78:79], v[104:105] op_sel_hi:[1,0] neg_lo:[0,1] neg_hi:[0,1]
	v_pk_add_f32 v[48:49], v[48:49], v[104:105] op_sel_hi:[1,0] neg_lo:[0,1] neg_hi:[0,1]
	v_cmp_neq_f32_e32 vcc, 1.0, v58
	s_cbranch_vccz .LBB0_1142

.LBB0_1143:
	s_mov_b32 s25, s24
	s_mov_b32 s24, s26
	s_mul_i32 s26, s26, 0x9000
	v_add_u32_e32 v138, s26, v122
	ds_read_b128 v[64:67], v138
	ds_read_b128 v[134:137], v138 offset:4608
	s_mul_i32 s26, s25, 0x9000
	s_waitcnt lgkmcnt(1)
	v_mfma_f32_32x32x16_bf16 v[48:63], v[64:67], v[80:83], v[32:47]
	v_mov_b64_e32 v[78:79], v[46:47]
	v_mov_b64_e32 v[76:77], v[44:45]
	v_mov_b64_e32 v[74:75], v[42:43]
	v_mov_b64_e32 v[72:73], v[40:41]
	v_mov_b64_e32 v[70:71], v[38:39]
	v_mov_b64_e32 v[68:69], v[36:37]
	v_mov_b64_e32 v[66:67], v[34:35]
	v_mov_b64_e32 v[64:65], v[32:33]
	s_waitcnt lgkmcnt(0)
	s_nop 0
	v_mfma_f32_32x32x16_bf16 v[64:79], v[134:137], v[80:83], v[64:79]
	ds_read_b128 v[134:137], v138 offset:32
	s_waitcnt lgkmcnt(0)
	v_mfma_f32_32x32x16_bf16 v[48:63], v[134:137], v[84:87], v[48:63]
	ds_read_b128 v[134:137], v138 offset:4640
	s_waitcnt lgkmcnt(0)
	v_mfma_f32_32x32x16_bf16 v[64:79], v[134:137], v[84:87], v[64:79]
	ds_read_b128 v[134:137], v138 offset:64
	s_waitcnt lgkmcnt(0)
	v_mfma_f32_32x32x16_bf16 v[48:63], v[134:137], v[88:91], v[48:63]
	ds_read_b128 v[134:137], v138 offset:4672
	s_waitcnt lgkmcnt(0)
	v_mfma_f32_32x32x16_bf16 v[64:79], v[134:137], v[88:91], v[64:79]
	ds_read_b128 v[134:137], v138 offset:96
	s_waitcnt lgkmcnt(0)
	v_mfma_f32_32x32x16_bf16 v[48:63], v[134:137], v[92:95], v[48:63]
	ds_read_b128 v[134:137], v138 offset:4704
	v_add_u32_e32 v138, s26, v127
	v_add_u32_e32 v139, 0x4000, v138
	v_add_u32_e32 v138, 0x5000, v138
	s_waitcnt lgkmcnt(0)
	v_mfma_f32_32x32x16_bf16 v[64:79], v[134:137], v[92:95], v[64:79]
	ds_read2_b64 v[134:137], v139 offset0:128 offset1:130
	s_waitcnt lgkmcnt(0)
	v_mfma_f32_32x32x16_bf16 v[16:31], v[134:137], v[116:119], v[16:31]
	ds_read2_b64 v[134:137], v138 offset0:192 offset1:194
	s_waitcnt lgkmcnt(0)
	v_mfma_f32_32x32x16_bf16 v[0:15], v[134:137], v[116:119], v[0:15]
	ds_read2_b64 v[116:119], v139 offset0:132 offset1:134
	s_waitcnt lgkmcnt(0)
	v_mfma_f32_32x32x16_bf16 v[16:31], v[116:119], v[112:115], v[16:31]
	ds_read2_b64 v[116:119], v138 offset0:196 offset1:198
	s_waitcnt lgkmcnt(0)
	v_mfma_f32_32x32x16_bf16 v[0:15], v[116:119], v[112:115], v[0:15]
	ds_read2_b64 v[112:115], v139 offset0:136 offset1:138
	ds_read2_b64 v[116:119], v138 offset0:200 offset1:202
	ds_read2_b64 v[134:137], v139 offset0:140 offset1:142
	ds_read2_b64 v[138:141], v138 offset0:204 offset1:206
	s_nop 15
	s_nop 7
	s_waitcnt lgkmcnt(3)
	v_mfma_f32_32x32x16_bf16 v[16:31], v[112:115], v[108:111], v[16:31]
	v_max3_f32 v112, v48, v49, v64
	s_nop 0
	v_max3_f32 v112, v112, v65, v50
	s_nop 0
	v_max3_f32 v112, v112, v66, v66
	s_nop 0
	v_max3_f32 v112, v112, v51, v67
	s_waitcnt lgkmcnt(2)
	v_mfma_f32_32x32x16_bf16 v[0:15], v[116:119], v[108:111], v[0:15]
	v_max3_f32 v112, v112, v52, v68
	s_nop 0
	v_max3_f32 v112, v112, v53, v69
	s_nop 0
	v_max3_f32 v112, v112, v54, v70
	s_nop 0
	v_max3_f32 v108, v112, v55, v71
	s_waitcnt lgkmcnt(1)
	v_mfma_f32_32x32x16_bf16 v[16:31], v[134:137], v[104:107], v[16:31]
	v_max3_f32 v108, v108, v56, v72
	s_nop 0
	v_max3_f32 v108, v108, v57, v73
	s_nop 0
	v_max3_f32 v108, v108, v58, v74
	s_nop 0
	v_max3_f32 v108, v108, v59, v75
	s_waitcnt lgkmcnt(0)
	v_mfma_f32_32x32x16_bf16 v[0:15], v[138:141], v[104:107], v[0:15]
	v_max3_f32 v108, v108, v60, v76
	s_nop 0
	v_max3_f32 v108, v108, v61, v77
	s_nop 0
	v_max3_f32 v108, v108, v62, v78
	s_nop 0
	v_max3_f32 v108, v108, v63, v79
	ds_bpermute_b32 v109, v125, v108
	v_max_f32_e32 v108, v108, v108
	s_waitcnt lgkmcnt(0)
	v_max_f32_e32 v109, v109, v109
	v_max_f32_e32 v108, v108, v109
	v_cmp_lt_f32_e32 vcc, 0x41000000, v108
	s_cbranch_vccz .LBB0_1150
	v_max_f32_e32 v32, v108, v108
	v_max_f32_e32 v34, 0, v32
	v_exp_f32_e64 v104, -v34
	v_add_f32_e32 v130, v130, v34
	v_xor_b32_e32 v32, 0x80000000, v130
	v_pk_add_f32 v[48:49], v[48:49], v[34:35] op_sel_hi:[1,0] neg_lo:[0,1] neg_hi:[0,1]
	v_pk_add_f32 v[64:65], v[64:65], v[34:35] op_sel_hi:[1,0] neg_lo:[0,1] neg_hi:[0,1]
	v_pk_add_f32 v[50:51], v[50:51], v[34:35] op_sel_hi:[1,0] neg_lo:[0,1] neg_hi:[0,1]
	v_pk_add_f32 v[66:67], v[66:67], v[34:35] op_sel_hi:[1,0] neg_lo:[0,1] neg_hi:[0,1]
	v_pk_add_f32 v[52:53], v[52:53], v[34:35] op_sel_hi:[1,0] neg_lo:[0,1] neg_hi:[0,1]
	v_pk_add_f32 v[68:69], v[68:69], v[34:35] op_sel_hi:[1,0] neg_lo:[0,1] neg_hi:[0,1]
	v_pk_add_f32 v[54:55], v[54:55], v[34:35] op_sel_hi:[1,0] neg_lo:[0,1] neg_hi:[0,1]
	v_pk_add_f32 v[70:71], v[70:71], v[34:35] op_sel_hi:[1,0] neg_lo:[0,1] neg_hi:[0,1]
	v_pk_add_f32 v[56:57], v[56:57], v[34:35] op_sel_hi:[1,0] neg_lo:[0,1] neg_hi:[0,1]
	v_pk_add_f32 v[72:73], v[72:73], v[34:35] op_sel_hi:[1,0] neg_lo:[0,1] neg_hi:[0,1]
	v_pk_add_f32 v[58:59], v[58:59], v[34:35] op_sel_hi:[1,0] neg_lo:[0,1] neg_hi:[0,1]
	v_pk_add_f32 v[74:75], v[74:75], v[34:35] op_sel_hi:[1,0] neg_lo:[0,1] neg_hi:[0,1]
	v_pk_add_f32 v[60:61], v[60:61], v[34:35] op_sel_hi:[1,0] neg_lo:[0,1] neg_hi:[0,1]
	v_pk_add_f32 v[76:77], v[76:77], v[34:35] op_sel_hi:[1,0] neg_lo:[0,1] neg_hi:[0,1]
	v_pk_add_f32 v[62:63], v[62:63], v[34:35] op_sel_hi:[1,0] neg_lo:[0,1] neg_hi:[0,1]
	v_pk_add_f32 v[78:79], v[78:79], v[34:35] op_sel_hi:[1,0] neg_lo:[0,1] neg_hi:[0,1]
	v_mov_b32_e32 v33, v32
	v_mov_b32_e32 v34, v32
	v_mov_b32_e32 v35, v32
	v_mov_b32_e32 v36, v32
	v_mov_b32_e32 v37, v32
	v_mov_b32_e32 v38, v32
	v_mov_b32_e32 v39, v32
	v_mov_b32_e32 v40, v32
	v_mov_b32_e32 v41, v32
	v_mov_b32_e32 v42, v32
	v_mov_b32_e32 v43, v32
	v_mov_b32_e32 v44, v32
	v_mov_b32_e32 v45, v32
	v_mov_b32_e32 v46, v32
	v_mov_b32_e32 v47, v32
	v_cmp_neq_f32_e32 vcc, 1.0, v104
	s_cbranch_vccz .LBB0_1146

.LBB0_1153:
	s_mul_i32 s70, s84, 0x9000
	v_add_u32_e32 v208, s70, v154
	s_mov_b32 s71, s65
	s_mul_i32 s68, s71, 0x9000
	s_mov_b32 s65, s84
	v_add_u32_e32 v209, s68, v155
	v_add_u32_e32 v210, 0x4000, v209
	v_add_u32_e32 v211, 0x5000, v209
	ds_read_b128 v[156:159], v208
	ds_read_b128 v[160:163], v208 offset:4608
	ds_read_b128 v[164:167], v208 offset:32
	ds_read_b128 v[168:171], v208 offset:4640
	ds_read_b128 v[172:175], v208 offset:64
	ds_read_b128 v[176:179], v208 offset:4672
	ds_read_b128 v[184:187], v208 offset:96
	ds_read_b128 v[188:191], v208 offset:4704
	ds_read2_b64 v[192:195], v210 offset0:128 offset1:130
	ds_read2_b64 v[196:199], v211 offset0:192 offset1:194
	ds_read2_b64 v[200:203], v210 offset0:132 offset1:134
	ds_read2_b64 v[204:207], v211 offset0:196 offset1:198
	s_waitcnt lgkmcnt(10)
	v_mfma_f32_32x32x16_bf16 v[64:79], v[156:159], v[108:111], v[32:47]
	ds_read2_b64 v[156:159], v210 offset0:136 offset1:138
	s_mul_i32 s72, s66, 0x9000
	s_add_i32 s73, s72, 0
	v_add3_u32 v218, s73, v150, v151
	v_add3_u32 v219, s73, v152, v153
	v_mfma_f32_32x32x16_bf16 v[80:95], v[160:163], v[108:111], v[32:47]
	ds_read2_b64 v[160:163], v211 offset0:200 offset1:202
	s_waitcnt vmcnt(0)
	ds_write_b128 v218, v[116:119]
	ds_write_b128 v219, v[124:127] offset:17408
	s_waitcnt lgkmcnt(12)
	v_mfma_f32_32x32x16_bf16 v[64:79], v[164:167], v[104:107], v[64:79]
	ds_read2_b64 v[164:167], v210 offset0:140 offset1:142
	v_mfma_f32_32x32x16_bf16 v[80:95], v[168:171], v[104:107], v[80:95]
	ds_read2_b64 v[168:171], v211 offset0:204 offset1:206
	s_waitcnt lgkmcnt(12)
	v_mfma_f32_32x32x16_bf16 v[64:79], v[172:175], v[100:103], v[64:79]
	v_mfma_f32_32x32x16_bf16 v[80:95], v[176:179], v[100:103], v[80:95]
	s_waitcnt lgkmcnt(10)
	v_mfma_f32_32x32x16_bf16 v[64:79], v[184:187], v[96:99], v[64:79]
	v_mfma_f32_32x32x16_bf16 v[80:95], v[188:191], v[96:99], v[80:95]
	s_waitcnt lgkmcnt(8)
	v_mfma_f32_32x32x16_bf16 v[16:31], v[192:195], v[134:137], v[16:31]
	v_mfma_f32_32x32x16_bf16 v[0:15], v[196:199], v[134:137], v[0:15]
	s_add_i32 s68, s25, -2
	s_cmp_gt_u32 s68, 33
	s_cbranch_scc1 .Lag_nogl
	s_cmp_lt_u32 s68, 30
	s_cselect_b64 s[74:75], -1, 0
	s_and_b64 s[76:77], s[74:75], exec
	s_cselect_b32 s68, 0, 0xffffffe0
	s_add_i32 s68, s68, s25
	s_and_b64 s[76:77], s[74:75], exec
	s_cselect_b32 s73, s21, s27
	s_cselect_b32 s78, s20, s26
	s_lshl_b64 s[76:77], s[68:69], 14
	s_add_u32 s76, s78, s76
	s_addc_u32 s77, s73, s77
	s_and_b64 s[78:79], s[74:75], exec
	s_cselect_b32 s73, s23, s64
	s_cselect_b32 s80, s22, s63
	s_lshl_b32 s68, s68, 6
	s_lshl_b64 s[78:79], s[68:69], 1
	s_add_u32 s78, s80, s78
	s_addc_u32 s79, s73, s79
	v_lshl_add_u64 v[222:223], v[142:143], 1, s[76:77]
	s_and_b64 s[74:75], s[74:75], exec
	v_lshl_add_u64 v[222:223], v[144:145], 1, v[222:223]
	s_cselect_b32 s68, 11, 8
	global_load_dwordx4 v[116:119], v[222:223], off
	v_lshlrev_b64 v[222:223], s68, v[146:147]
	v_lshl_add_u64 v[222:223], v[222:223], 1, s[78:79]
	v_lshl_add_u64 v[222:223], v[222:223], 0, v[128:129]
	global_load_dwordx4 v[124:127], v[222:223], off
.Lag_nogl:
	s_waitcnt lgkmcnt(6)
	v_mfma_f32_32x32x16_bf16 v[16:31], v[200:203], v[130:133], v[16:31]
	v_mfma_f32_32x32x16_bf16 v[0:15], v[204:207], v[130:133], v[0:15]
	s_waitcnt lgkmcnt(4)
	v_mfma_f32_32x32x16_bf16 v[16:31], v[156:159], v[120:123], v[16:31]
	v_mfma_f32_32x32x16_bf16 v[0:15], v[160:163], v[120:123], v[0:15]
	v_max3_f32 v212, v64, v80, v68
	v_max3_f32 v213, v65, v81, v69
	v_max3_f32 v214, v66, v82, v70
	v_max3_f32 v215, v67, v83, v71
	v_max3_f32 v212, v212, v84, v72
	v_max3_f32 v213, v213, v85, v73
	v_max3_f32 v214, v214, v86, v74
	v_max3_f32 v215, v215, v87, v75
	s_waitcnt lgkmcnt(0)
	v_mfma_f32_32x32x16_bf16 v[16:31], v[164:167], v[112:115], v[16:31]
	v_max3_f32 v212, v212, v88, v76
	v_max3_f32 v213, v213, v89, v77
	v_max3_f32 v214, v214, v90, v78
	v_max3_f32 v215, v215, v91, v79
	v_max_f32_e32 v212, v212, v92
	v_max_f32_e32 v213, v213, v93
	v_max_f32_e32 v214, v214, v94
	v_max_f32_e32 v215, v215, v95
	v_mfma_f32_32x32x16_bf16 v[0:15], v[168:171], v[112:115], v[0:15]
	v_max3_f32 v212, v212, v213, v214
	v_max_f32_e32 v212, v212, v215
	v_mov_b32_e32 v216, v212
	v_mov_b32_e32 v217, v212
	s_nop 1
	v_permlane32_swap_b32_e32 v216, v217
	v_max_f32_e32 v212, v216, v217
	v_cmp_lt_f32_e32 vcc, 0x41000000, v212
	s_cbranch_vccz .Lag_common
	s_nop 7
	s_nop 3
	v_max_f32_e32 v32, v212, v212
	v_max_f32_e32 v32, 0, v32
	v_exp_f32_e64 v112, -v32
	v_add_f32_e32 v149, v149, v32
	v_xor_b32_e32 v48, 0x80000000, v149
	v_pk_add_f32 v[64:65], v[64:65], v[32:33] op_sel_hi:[1,0] neg_lo:[0,1] neg_hi:[0,1]
	v_pk_add_f32 v[80:81], v[80:81], v[32:33] op_sel_hi:[1,0] neg_lo:[0,1] neg_hi:[0,1]
	v_pk_add_f32 v[66:67], v[66:67], v[32:33] op_sel_hi:[1,0] neg_lo:[0,1] neg_hi:[0,1]
	v_pk_add_f32 v[82:83], v[82:83], v[32:33] op_sel_hi:[1,0] neg_lo:[0,1] neg_hi:[0,1]
	v_pk_add_f32 v[68:69], v[68:69], v[32:33] op_sel_hi:[1,0] neg_lo:[0,1] neg_hi:[0,1]
	v_pk_add_f32 v[84:85], v[84:85], v[32:33] op_sel_hi:[1,0] neg_lo:[0,1] neg_hi:[0,1]
	v_pk_add_f32 v[70:71], v[70:71], v[32:33] op_sel_hi:[1,0] neg_lo:[0,1] neg_hi:[0,1]
	v_pk_add_f32 v[86:87], v[86:87], v[32:33] op_sel_hi:[1,0] neg_lo:[0,1] neg_hi:[0,1]
	v_pk_add_f32 v[72:73], v[72:73], v[32:33] op_sel_hi:[1,0] neg_lo:[0,1] neg_hi:[0,1]
	v_pk_add_f32 v[88:89], v[88:89], v[32:33] op_sel_hi:[1,0] neg_lo:[0,1] neg_hi:[0,1]
	v_pk_add_f32 v[74:75], v[74:75], v[32:33] op_sel_hi:[1,0] neg_lo:[0,1] neg_hi:[0,1]
	v_pk_add_f32 v[90:91], v[90:91], v[32:33] op_sel_hi:[1,0] neg_lo:[0,1] neg_hi:[0,1]
	v_pk_add_f32 v[76:77], v[76:77], v[32:33] op_sel_hi:[1,0] neg_lo:[0,1] neg_hi:[0,1]
	v_pk_add_f32 v[92:93], v[92:93], v[32:33] op_sel_hi:[1,0] neg_lo:[0,1] neg_hi:[0,1]
	v_pk_add_f32 v[78:79], v[78:79], v[32:33] op_sel_hi:[1,0] neg_lo:[0,1] neg_hi:[0,1]
	v_pk_add_f32 v[94:95], v[94:95], v[32:33] op_sel_hi:[1,0] neg_lo:[0,1] neg_hi:[0,1]
	v_mov_b32_e32 v49, v48
	v_mov_b32_e32 v50, v48
	v_mov_b32_e32 v51, v48
	v_mov_b32_e32 v52, v48
	v_mov_b32_e32 v53, v48
	v_mov_b32_e32 v54, v48
	v_mov_b32_e32 v55, v48
	v_mov_b32_e32 v56, v48
	v_mov_b32_e32 v57, v48
	v_mov_b32_e32 v58, v48
	v_mov_b32_e32 v59, v48
	v_mov_b32_e32 v60, v48
	v_mov_b32_e32 v61, v48
	v_mov_b32_e32 v62, v48
	v_mov_b32_e32 v63, v48
	v_mov_b32_e32 v32, v48
	v_mov_b32_e32 v33, v48
	v_mov_b32_e32 v34, v48
	v_mov_b32_e32 v35, v48
	v_mov_b32_e32 v36, v48
	v_mov_b32_e32 v37, v48
	v_mov_b32_e32 v38, v48
	v_mov_b32_e32 v39, v48
	v_mov_b32_e32 v40, v48
	v_mov_b32_e32 v41, v48
	v_mov_b32_e32 v42, v48
	v_mov_b32_e32 v43, v48
	v_mov_b32_e32 v44, v48
	v_mov_b32_e32 v45, v48
	v_mov_b32_e32 v46, v48
	v_mov_b32_e32 v47, v48
	v_cmp_neq_f32_e32 vcc, 1.0, v112
	s_cbranch_vccz .Lag_rjoin
	v_pk_mul_f32 v[30:31], v[30:31], v[112:113] op_sel_hi:[1,0]
	v_pk_mul_f32 v[28:29], v[28:29], v[112:113] op_sel_hi:[1,0]
	v_pk_mul_f32 v[26:27], v[26:27], v[112:113] op_sel_hi:[1,0]
	v_pk_mul_f32 v[24:25], v[24:25], v[112:113] op_sel_hi:[1,0]
	v_pk_mul_f32 v[22:23], v[22:23], v[112:113] op_sel_hi:[1,0]
	v_pk_mul_f32 v[20:21], v[20:21], v[112:113] op_sel_hi:[1,0]
	v_pk_mul_f32 v[18:19], v[18:19], v[112:113] op_sel_hi:[1,0]
	v_pk_mul_f32 v[16:17], v[16:17], v[112:113] op_sel_hi:[1,0]
	v_pk_mul_f32 v[14:15], v[14:15], v[112:113] op_sel_hi:[1,0]
	v_pk_mul_f32 v[12:13], v[12:13], v[112:113] op_sel_hi:[1,0]
	v_pk_mul_f32 v[10:11], v[10:11], v[112:113] op_sel_hi:[1,0]
	v_pk_mul_f32 v[8:9], v[8:9], v[112:113] op_sel_hi:[1,0]
	v_pk_mul_f32 v[6:7], v[6:7], v[112:113] op_sel_hi:[1,0]
	v_pk_mul_f32 v[4:5], v[4:5], v[112:113] op_sel_hi:[1,0]
	v_pk_mul_f32 v[2:3], v[2:3], v[112:113] op_sel_hi:[1,0]
	v_pk_mul_f32 v[0:1], v[0:1], v[112:113] op_sel_hi:[1,0]

.Lag_common:
	v_exp_f32_e32 v64, v64
	v_exp_f32_e32 v80, v80
	v_exp_f32_e32 v221, v65
	v_exp_f32_e32 v81, v81
	v_exp_f32_e32 v66, v66
	v_exp_f32_e32 v82, v82
	v_exp_f32_e32 v67, v67
	v_exp_f32_e32 v83, v83
	v_add_f32_e32 v65, v80, v64
	v_exp_f32_e32 v68, v68
	v_exp_f32_e32 v84, v84
	v_add_f32_e32 v65, 0, v65
	v_add_f32_e32 v227, v81, v221
	v_exp_f32_e32 v69, v69
	v_exp_f32_e32 v85, v85
	v_add_f32_e32 v65, v227, v65
	v_add_f32_e32 v227, v82, v66
	v_exp_f32_e32 v70, v70
	v_exp_f32_e32 v86, v86
	v_add_f32_e32 v65, v227, v65
	v_add_f32_e32 v227, v83, v67
	v_exp_f32_e32 v71, v71
	v_exp_f32_e32 v87, v87
	v_add_f32_e32 v65, v227, v65
	v_add_f32_e32 v227, v84, v68
	v_exp_f32_e32 v72, v72
	v_exp_f32_e32 v88, v88
	v_add_f32_e32 v65, v227, v65
	v_add_f32_e32 v227, v85, v69
	v_exp_f32_e32 v73, v73
	v_exp_f32_e32 v89, v89
	v_add_f32_e32 v65, v227, v65
	v_add_f32_e32 v227, v86, v70
	v_exp_f32_e32 v74, v74
	v_exp_f32_e32 v90, v90
	v_add_f32_e32 v65, v227, v65
	v_add_f32_e32 v227, v87, v71
	v_exp_f32_e32 v75, v75
	v_exp_f32_e32 v91, v91
	v_add_f32_e32 v65, v227, v65
	v_add_f32_e32 v227, v88, v72
	v_exp_f32_e32 v76, v76
	v_exp_f32_e32 v92, v92
	v_add_f32_e32 v65, v227, v65
	v_add_f32_e32 v227, v89, v73
	v_exp_f32_e32 v77, v77
	v_exp_f32_e32 v93, v93
	v_add_f32_e32 v65, v227, v65
	v_add_f32_e32 v227, v90, v74
	v_exp_f32_e32 v78, v78
	v_exp_f32_e32 v94, v94
	v_add_f32_e32 v65, v227, v65
	v_add_f32_e32 v227, v91, v75
	v_exp_f32_e32 v79, v79
	v_exp_f32_e32 v95, v95
	v_add_f32_e32 v65, v227, v65
	v_add_f32_e32 v227, v92, v76
	v_add_f32_e32 v65, v227, v65
	v_add_f32_e32 v227, v93, v77
	v_add_f32_e32 v65, v227, v65
	v_add_f32_e32 v227, v94, v78
	v_add_f32_e32 v65, v227, v65
	v_add_f32_e32 v227, v95, v79
	v_add_f32_e32 v65, v227, v65
	v_add_f32_e32 v65, v148, v65
	v_cvt_pk_bf16_f32 v134, v64, v221
	v_cvt_pk_bf16_f32 v135, v66, v67
	v_cvt_pk_bf16_f32 v136, v68, v69
	v_cvt_pk_bf16_f32 v137, v70, v71
	v_cvt_pk_bf16_f32 v120, v80, v81
	v_cvt_pk_bf16_f32 v121, v82, v83
	v_cvt_pk_bf16_f32 v122, v84, v85
	v_cvt_pk_bf16_f32 v123, v86, v87
	v_cvt_pk_bf16_f32 v130, v72, v73
	v_cvt_pk_bf16_f32 v131, v74, v75
	v_cvt_pk_bf16_f32 v132, v76, v77
	v_cvt_pk_bf16_f32 v133, v78, v79
	v_cvt_pk_bf16_f32 v112, v88, v89
	v_cvt_pk_bf16_f32 v113, v90, v91
	v_cvt_pk_bf16_f32 v114, v92, v93
	v_cvt_pk_bf16_f32 v115, v94, v95

.LBB0_1161:
	v_add_u32_e32 v64, s72, v154
	ds_read_b128 v[66:69], v64
	s_waitcnt lgkmcnt(0)
	v_mfma_f32_32x32x16_bf16 v[32:47], v[66:69], v[108:111], v[48:63]
	ds_read_b128 v[66:69], v64 offset:4608
	s_waitcnt lgkmcnt(0)
	v_mfma_f32_32x32x16_bf16 v[48:63], v[66:69], v[108:111], v[48:63]
	ds_read_b128 v[66:69], v64 offset:32
	s_waitcnt lgkmcnt(0)
	v_mfma_f32_32x32x16_bf16 v[32:47], v[66:69], v[104:107], v[32:47]
	ds_read_b128 v[66:69], v64 offset:4640
	s_waitcnt lgkmcnt(0)
	v_mfma_f32_32x32x16_bf16 v[48:63], v[66:69], v[104:107], v[48:63]
	ds_read_b128 v[66:69], v64 offset:64
	s_waitcnt lgkmcnt(0)
	v_mfma_f32_32x32x16_bf16 v[32:47], v[66:69], v[100:103], v[32:47]
	ds_read_b128 v[66:69], v64 offset:4672
	s_waitcnt lgkmcnt(0)
	v_mfma_f32_32x32x16_bf16 v[48:63], v[66:69], v[100:103], v[48:63]
	ds_read_b128 v[66:69], v64 offset:96
	s_waitcnt lgkmcnt(0)
	v_mfma_f32_32x32x16_bf16 v[32:47], v[66:69], v[96:99], v[32:47]
	ds_read_b128 v[66:69], v64 offset:4704
	v_add_u32_e32 v64, s70, v155
	v_add_u32_e32 v74, 0x4000, v64
	v_add_u32_e32 v64, 0x5000, v64
	s_waitcnt lgkmcnt(0)
	v_mfma_f32_32x32x16_bf16 v[48:63], v[66:69], v[96:99], v[48:63]
	ds_read2_b64 v[66:69], v74 offset0:128 offset1:130
	s_waitcnt lgkmcnt(0)
	v_mfma_f32_32x32x16_bf16 v[16:31], v[66:69], v[134:137], v[16:31]
	ds_read2_b64 v[66:69], v64 offset0:192 offset1:194
	s_waitcnt lgkmcnt(0)
	v_mfma_f32_32x32x16_bf16 v[0:15], v[66:69], v[134:137], v[0:15]
	ds_read2_b64 v[66:69], v74 offset0:132 offset1:134
	s_waitcnt lgkmcnt(0)
	v_mfma_f32_32x32x16_bf16 v[16:31], v[66:69], v[130:133], v[16:31]
	ds_read2_b64 v[66:69], v64 offset0:196 offset1:198
	s_waitcnt lgkmcnt(0)
	v_mfma_f32_32x32x16_bf16 v[0:15], v[66:69], v[130:133], v[0:15]
	ds_read2_b64 v[66:69], v74 offset0:136 offset1:138
	ds_read2_b64 v[70:73], v64 offset0:200 offset1:202
	ds_read2_b64 v[74:77], v74 offset0:140 offset1:142
	ds_read2_b64 v[78:81], v64 offset0:204 offset1:206
	s_nop 15
	s_nop 7
	s_nop 0
	v_max3_f32 v64, v32, v33, v48
	s_nop 0
	v_max3_f32 v64, v64, v49, v34
	s_nop 0
	v_max3_f32 v64, v64, v50, v50
	s_waitcnt lgkmcnt(3)
	v_mfma_f32_32x32x16_bf16 v[16:31], v[66:69], v[120:123], v[16:31]
	v_max3_f32 v64, v64, v35, v51
	s_nop 0
	v_max3_f32 v64, v64, v36, v52
	s_nop 0
	v_max3_f32 v64, v64, v37, v53
	s_nop 0
	v_max3_f32 v64, v64, v38, v54
	s_waitcnt lgkmcnt(2)
	v_mfma_f32_32x32x16_bf16 v[0:15], v[70:73], v[120:123], v[0:15]
	v_max3_f32 v64, v64, v39, v55
	s_nop 0
	v_max3_f32 v64, v64, v40, v56
	s_nop 0
	v_max3_f32 v64, v64, v41, v57
	s_nop 0
	v_max3_f32 v64, v64, v42, v58
	s_waitcnt lgkmcnt(1)
	v_mfma_f32_32x32x16_bf16 v[16:31], v[74:77], v[112:115], v[16:31]
	v_max3_f32 v64, v64, v43, v59
	s_nop 0
	v_max3_f32 v64, v64, v44, v60
	s_nop 0
	v_max3_f32 v64, v64, v45, v61
	s_nop 0
	v_max3_f32 v64, v64, v46, v62
	s_waitcnt lgkmcnt(0)
	v_mfma_f32_32x32x16_bf16 v[0:15], v[78:81], v[112:115], v[0:15]
	v_max3_f32 v64, v64, v47, v63
	ds_bpermute_b32 v66, v141, v64
	v_max_f32_e32 v64, v64, v64
	s_waitcnt lgkmcnt(0)
	v_max_f32_e32 v66, v66, v66
	v_max_f32_e32 v64, v64, v66
	v_cmp_lt_f32_e32 vcc, 0x41000000, v64
	s_cbranch_vccz .LBB0_1164
	v_max_f32_e32 v64, v64, v64
	v_max_f32_e32 v66, 0, v64
	v_exp_f32_e64 v64, -v66
	v_pk_add_f32 v[32:33], v[32:33], v[66:67] op_sel_hi:[1,0] neg_lo:[0,1] neg_hi:[0,1]
	v_pk_add_f32 v[48:49], v[48:49], v[66:67] op_sel_hi:[1,0] neg_lo:[0,1] neg_hi:[0,1]
	v_pk_add_f32 v[34:35], v[34:35], v[66:67] op_sel_hi:[1,0] neg_lo:[0,1] neg_hi:[0,1]
	v_pk_add_f32 v[50:51], v[50:51], v[66:67] op_sel_hi:[1,0] neg_lo:[0,1] neg_hi:[0,1]
	v_pk_add_f32 v[36:37], v[36:37], v[66:67] op_sel_hi:[1,0] neg_lo:[0,1] neg_hi:[0,1]
	v_pk_add_f32 v[52:53], v[52:53], v[66:67] op_sel_hi:[1,0] neg_lo:[0,1] neg_hi:[0,1]
	v_pk_add_f32 v[38:39], v[38:39], v[66:67] op_sel_hi:[1,0] neg_lo:[0,1] neg_hi:[0,1]
	v_pk_add_f32 v[54:55], v[54:55], v[66:67] op_sel_hi:[1,0] neg_lo:[0,1] neg_hi:[0,1]
	v_pk_add_f32 v[40:41], v[40:41], v[66:67] op_sel_hi:[1,0] neg_lo:[0,1] neg_hi:[0,1]
	v_pk_add_f32 v[56:57], v[56:57], v[66:67] op_sel_hi:[1,0] neg_lo:[0,1] neg_hi:[0,1]
	v_pk_add_f32 v[42:43], v[42:43], v[66:67] op_sel_hi:[1,0] neg_lo:[0,1] neg_hi:[0,1]
	v_pk_add_f32 v[58:59], v[58:59], v[66:67] op_sel_hi:[1,0] neg_lo:[0,1] neg_hi:[0,1]
	v_pk_add_f32 v[44:45], v[44:45], v[66:67] op_sel_hi:[1,0] neg_lo:[0,1] neg_hi:[0,1]
	v_pk_add_f32 v[60:61], v[60:61], v[66:67] op_sel_hi:[1,0] neg_lo:[0,1] neg_hi:[0,1]
	v_pk_add_f32 v[46:47], v[46:47], v[66:67] op_sel_hi:[1,0] neg_lo:[0,1] neg_hi:[0,1]
	v_pk_add_f32 v[62:63], v[62:63], v[66:67] op_sel_hi:[1,0] neg_lo:[0,1] neg_hi:[0,1]
	s_branch .LBB0_1165

.LBB0_1171:
	s_mul_i32 s68, s85, 0x9000
	v_add_u32_e32 v193, s68, v191
	s_mov_b32 s72, s70
	s_mul_i32 s68, s72, 0x9000
	s_mov_b32 s70, s85
	v_add_u32_e32 v221, s68, v192
	v_add_u32_e32 v222, 0x4000, v221
	v_add_u32_e32 v223, 0x5000, v221
	v_add_u32_e32 v227, 0x6800, v221
	v_add_u32_e32 v232, 0x7800, v221
	ds_read_b128 v[194:197], v193
	ds_read_b128 v[198:201], v193 offset:8704
	ds_read_b128 v[202:205], v193 offset:32
	ds_read_b128 v[206:209], v193 offset:8736
	ds_read_b128 v[210:213], v193 offset:64
	ds_read_b128 v[214:217], v193 offset:8768
	ds_read_b128 v[238:241], v193 offset:96
	s_waitcnt lgkmcnt(5)
	v_mfma_f32_32x32x16_bf16 v[80:95], v[194:197], v[112:115], v[64:79]
	ds_read_b128 v[194:197], v193 offset:8800
	s_mul_i32 s73, s71, 0x9000
	s_add_i32 s73, s73, 0
	v_add_u32_e32 v249, s73, v188
	v_add3_u32 v250, s73, v184, v185
	v_add_u32_e32 v251, v249, v190
	v_add_u32_e32 v249, v249, v189
	v_add3_u32 v218, s73, v186, v187
	v_mfma_f32_32x32x16_bf16 v[96:111], v[198:201], v[112:115], v[64:79]
	ds_read2_b64 v[198:201], v222 offset0:128 offset1:130
	s_waitcnt vmcnt(0)
	ds_write_b128 v250, v[130:133]
	ds_write_b128 v218, v[134:137]
	ds_write_b128 v249, v[138:141] offset:17408
	ds_write_b128 v251, v[142:145] offset:17408
	s_waitcnt lgkmcnt(9)
	v_mfma_f32_32x32x16_bf16 v[80:95], v[202:205], v[116:119], v[80:95]
	ds_read2_b64 v[202:205], v223 offset0:192 offset1:194
	v_mfma_f32_32x32x16_bf16 v[96:111], v[206:209], v[116:119], v[96:111]
	ds_read2_b64 v[206:209], v227 offset0:0 offset1:2
	s_waitcnt lgkmcnt(9)
	v_mfma_f32_32x32x16_bf16 v[80:95], v[210:213], v[120:123], v[80:95]
	ds_read2_b64 v[210:213], v232 offset0:64 offset1:66
	v_mfma_f32_32x32x16_bf16 v[96:111], v[214:217], v[120:123], v[96:111]
	ds_read2_b64 v[214:217], v222 offset0:132 offset1:134
	s_waitcnt lgkmcnt(9)
	v_mfma_f32_32x32x16_bf16 v[80:95], v[238:241], v[124:127], v[80:95]
	ds_read2_b64 v[238:241], v223 offset0:196 offset1:198
	v_mfma_f32_32x32x16_bf16 v[96:111], v[194:197], v[124:127], v[96:111]
	ds_read2_b64 v[194:197], v227 offset0:4 offset1:6
	s_waitcnt lgkmcnt(5)
	v_mfma_f32_32x32x16_bf16 v[48:63], v[198:201], v[158:161], v[48:63]
	ds_read2_b64 v[198:201], v232 offset0:68 offset1:70
	v_mfma_f32_32x32x16_bf16 v[32:47], v[202:205], v[158:161], v[32:47]
	ds_read2_b64 v[202:205], v222 offset0:136 offset1:138
	s_add_i32 s68, s63, -2
	s_cmp_gt_u32 s68, 33
	s_cbranch_scc1 .Lad_nogl
	s_cmp_lt_u32 s68, 30
	s_cselect_b64 s[74:75], -1, 0
	s_and_b64 s[76:77], s[74:75], exec
	s_cselect_b32 s68, 0, 0xffffffe0
	s_add_i32 s68, s68, s63
	s_and_b64 s[76:77], s[74:75], exec
	s_cselect_b32 s73, s23, s65
	s_cselect_b32 s78, s22, s64
	s_lshl_b64 s[76:77], s[68:69], 16
	s_add_u32 s76, s78, s76
	s_addc_u32 s77, s73, s77
	s_and_b64 s[78:79], s[74:75], exec
	s_cselect_b32 s73, s25, s84
	s_cselect_b32 s80, s24, s66
	s_lshl_b32 s68, s68, 6
	s_lshl_b64 s[78:79], s[68:69], 1
	s_add_u32 s78, s80, s78
	s_addc_u32 s79, s73, s79
	s_and_b64 s[74:75], s[74:75], exec
	s_cselect_b32 s68, 11, 8
	v_lshl_add_u64 v[130:131], v[168:169], 1, s[76:77]
	v_lshl_add_u64 v[132:133], v[172:173], 1, s[76:77]
	v_lshl_add_u64 v[138:139], s[78:79], 0, v[128:129]
	v_lshlrev_b64 v[140:141], s68, v[176:177]
	v_lshlrev_b64 v[142:143], s68, v[178:179]
	v_lshl_add_u64 v[130:131], v[170:171], 1, v[130:131]
	v_lshl_add_u64 v[134:135], v[174:175], 1, v[132:133]
	v_lshl_add_u64 v[140:141], v[140:141], 1, v[138:139]
	v_lshl_add_u64 v[142:143], v[142:143], 1, v[138:139]
	global_load_dwordx4 v[130:133], v[130:131], off
	s_nop 0
	global_load_dwordx4 v[134:137], v[134:135], off
	s_nop 0
	global_load_dwordx4 v[138:141], v[140:141], off
	s_nop 0
	global_load_dwordx4 v[142:145], v[142:143], off
.Lad_nogl:
	s_waitcnt lgkmcnt(5)
	v_mfma_f32_32x32x16_bf16 v[16:31], v[206:209], v[158:161], v[16:31]
	ds_read2_b64 v[206:209], v223 offset0:200 offset1:202
	v_mfma_f32_32x32x16_bf16 v[0:15], v[210:213], v[158:161], v[0:15]
	ds_read2_b64 v[210:213], v227 offset0:8 offset1:10
	s_waitcnt lgkmcnt(5)
	v_mfma_f32_32x32x16_bf16 v[48:63], v[214:217], v[154:157], v[48:63]
	ds_read2_b64 v[214:217], v232 offset0:72 offset1:74
	v_max3_f32 v233, v80, v96, v84
	v_max3_f32 v234, v81, v97, v85
	v_max3_f32 v242, v82, v98, v86
	v_max3_f32 v243, v83, v99, v87
	v_max3_f32 v233, v233, v100, v88
	v_max3_f32 v234, v234, v101, v89
	v_mfma_f32_32x32x16_bf16 v[32:47], v[238:241], v[154:157], v[32:47]
	ds_read2_b64 v[238:241], v222 offset0:140 offset1:142
	v_max3_f32 v242, v242, v102, v90
	v_max3_f32 v243, v243, v103, v91
	v_max3_f32 v233, v233, v104, v92
	v_max3_f32 v234, v234, v105, v93
	v_max3_f32 v242, v242, v106, v94
	v_max3_f32 v243, v243, v107, v95
	s_waitcnt lgkmcnt(5)
	v_mfma_f32_32x32x16_bf16 v[16:31], v[194:197], v[154:157], v[16:31]
	ds_read2_b64 v[194:197], v223 offset0:204 offset1:206
	v_max_f32_e32 v233, v233, v108
	v_max_f32_e32 v234, v234, v109
	v_max_f32_e32 v242, v242, v110
	v_max_f32_e32 v243, v243, v111
	v_max3_f32 v233, v233, v234, v242
	v_max_f32_e32 v233, v233, v243
	v_mfma_f32_32x32x16_bf16 v[0:15], v[198:201], v[154:157], v[0:15]
	ds_read2_b64 v[198:201], v227 offset0:12 offset1:14
	v_mov_b32_e32 v246, v233
	v_mov_b32_e32 v247, v233
	s_nop 1
	v_permlane32_swap_b32_e32 v246, v247
	v_max_f32_e32 v233, v246, v247
	v_cmp_lt_f32_e32 vcc, 0x41000000, v233
	s_cbranch_vccz .Lad_common
	s_waitcnt lgkmcnt(5)
	v_mfma_f32_32x32x16_bf16 v[48:63], v[202:205], v[150:153], v[48:63]
	ds_read2_b64 v[202:205], v232 offset0:76 offset1:78
	v_mfma_f32_32x32x16_bf16 v[32:47], v[206:209], v[150:153], v[32:47]
	s_waitcnt lgkmcnt(4)
	v_mfma_f32_32x32x16_bf16 v[16:31], v[210:213], v[150:153], v[16:31]
	v_mfma_f32_32x32x16_bf16 v[0:15], v[214:217], v[150:153], v[0:15]
	s_waitcnt lgkmcnt(2)
	v_mfma_f32_32x32x16_bf16 v[48:63], v[238:241], v[146:149], v[48:63]
	v_mfma_f32_32x32x16_bf16 v[32:47], v[194:197], v[146:149], v[32:47]
	s_waitcnt lgkmcnt(0)
	v_mfma_f32_32x32x16_bf16 v[16:31], v[198:201], v[146:149], v[16:31]
	v_mfma_f32_32x32x16_bf16 v[0:15], v[202:205], v[146:149], v[0:15]
	s_nop 7
	s_nop 3
	v_max_f32_e32 v64, v233, v233
	v_max_f32_e32 v66, 0, v64
	v_exp_f32_e64 v146, -v66
	v_add_f32_e32 v181, v181, v66
	v_xor_b32_e32 v64, 0x80000000, v181
	v_pk_add_f32 v[80:81], v[80:81], v[66:67] op_sel_hi:[1,0] neg_lo:[0,1] neg_hi:[0,1]
	v_pk_add_f32 v[96:97], v[96:97], v[66:67] op_sel_hi:[1,0] neg_lo:[0,1] neg_hi:[0,1]
	v_pk_add_f32 v[82:83], v[82:83], v[66:67] op_sel_hi:[1,0] neg_lo:[0,1] neg_hi:[0,1]
	v_pk_add_f32 v[98:99], v[98:99], v[66:67] op_sel_hi:[1,0] neg_lo:[0,1] neg_hi:[0,1]
	v_pk_add_f32 v[84:85], v[84:85], v[66:67] op_sel_hi:[1,0] neg_lo:[0,1] neg_hi:[0,1]
	v_pk_add_f32 v[100:101], v[100:101], v[66:67] op_sel_hi:[1,0] neg_lo:[0,1] neg_hi:[0,1]
	v_pk_add_f32 v[86:87], v[86:87], v[66:67] op_sel_hi:[1,0] neg_lo:[0,1] neg_hi:[0,1]
	v_pk_add_f32 v[102:103], v[102:103], v[66:67] op_sel_hi:[1,0] neg_lo:[0,1] neg_hi:[0,1]
	v_pk_add_f32 v[88:89], v[88:89], v[66:67] op_sel_hi:[1,0] neg_lo:[0,1] neg_hi:[0,1]
	v_pk_add_f32 v[104:105], v[104:105], v[66:67] op_sel_hi:[1,0] neg_lo:[0,1] neg_hi:[0,1]
	v_pk_add_f32 v[90:91], v[90:91], v[66:67] op_sel_hi:[1,0] neg_lo:[0,1] neg_hi:[0,1]
	v_pk_add_f32 v[106:107], v[106:107], v[66:67] op_sel_hi:[1,0] neg_lo:[0,1] neg_hi:[0,1]
	v_pk_add_f32 v[92:93], v[92:93], v[66:67] op_sel_hi:[1,0] neg_lo:[0,1] neg_hi:[0,1]
	v_pk_add_f32 v[108:109], v[108:109], v[66:67] op_sel_hi:[1,0] neg_lo:[0,1] neg_hi:[0,1]
	v_pk_add_f32 v[94:95], v[94:95], v[66:67] op_sel_hi:[1,0] neg_lo:[0,1] neg_hi:[0,1]
	v_pk_add_f32 v[110:111], v[110:111], v[66:67] op_sel_hi:[1,0] neg_lo:[0,1] neg_hi:[0,1]
	v_mov_b32_e32 v65, v64
	v_mov_b32_e32 v66, v64
	v_mov_b32_e32 v67, v64
	v_mov_b32_e32 v68, v64
	v_mov_b32_e32 v69, v64
	v_mov_b32_e32 v70, v64
	v_mov_b32_e32 v71, v64
	v_mov_b32_e32 v72, v64
	v_mov_b32_e32 v73, v64
	v_mov_b32_e32 v74, v64
	v_mov_b32_e32 v75, v64
	v_mov_b32_e32 v76, v64
	v_mov_b32_e32 v77, v64
	v_mov_b32_e32 v78, v64
	v_mov_b32_e32 v79, v64
	v_cmp_neq_f32_e32 vcc, 1.0, v146
	s_cbranch_vccz .Lad_rjoin
	v_pk_mul_f32 v[62:63], v[62:63], v[146:147] op_sel_hi:[1,0]
	v_pk_mul_f32 v[60:61], v[60:61], v[146:147] op_sel_hi:[1,0]
	v_pk_mul_f32 v[58:59], v[58:59], v[146:147] op_sel_hi:[1,0]
	v_pk_mul_f32 v[56:57], v[56:57], v[146:147] op_sel_hi:[1,0]
	v_pk_mul_f32 v[54:55], v[54:55], v[146:147] op_sel_hi:[1,0]
	v_pk_mul_f32 v[52:53], v[52:53], v[146:147] op_sel_hi:[1,0]
	v_pk_mul_f32 v[50:51], v[50:51], v[146:147] op_sel_hi:[1,0]
	v_pk_mul_f32 v[48:49], v[48:49], v[146:147] op_sel_hi:[1,0]
	v_pk_mul_f32 v[46:47], v[46:47], v[146:147] op_sel_hi:[1,0]
	v_pk_mul_f32 v[44:45], v[44:45], v[146:147] op_sel_hi:[1,0]
	v_pk_mul_f32 v[42:43], v[42:43], v[146:147] op_sel_hi:[1,0]
	v_pk_mul_f32 v[40:41], v[40:41], v[146:147] op_sel_hi:[1,0]
	v_pk_mul_f32 v[38:39], v[38:39], v[146:147] op_sel_hi:[1,0]
	v_pk_mul_f32 v[36:37], v[36:37], v[146:147] op_sel_hi:[1,0]
	v_pk_mul_f32 v[34:35], v[34:35], v[146:147] op_sel_hi:[1,0]
	v_pk_mul_f32 v[32:33], v[32:33], v[146:147] op_sel_hi:[1,0]
	v_pk_mul_f32 v[30:31], v[30:31], v[146:147] op_sel_hi:[1,0]
	v_pk_mul_f32 v[28:29], v[28:29], v[146:147] op_sel_hi:[1,0]
	v_pk_mul_f32 v[26:27], v[26:27], v[146:147] op_sel_hi:[1,0]
	v_pk_mul_f32 v[24:25], v[24:25], v[146:147] op_sel_hi:[1,0]
	v_pk_mul_f32 v[22:23], v[22:23], v[146:147] op_sel_hi:[1,0]
	v_pk_mul_f32 v[20:21], v[20:21], v[146:147] op_sel_hi:[1,0]
	v_pk_mul_f32 v[18:19], v[18:19], v[146:147] op_sel_hi:[1,0]
	v_pk_mul_f32 v[16:17], v[16:17], v[146:147] op_sel_hi:[1,0]
	v_pk_mul_f32 v[14:15], v[14:15], v[146:147] op_sel_hi:[1,0]
	v_pk_mul_f32 v[12:13], v[12:13], v[146:147] op_sel_hi:[1,0]
	v_pk_mul_f32 v[10:11], v[10:11], v[146:147] op_sel_hi:[1,0]
	v_pk_mul_f32 v[8:9], v[8:9], v[146:147] op_sel_hi:[1,0]
	v_pk_mul_f32 v[6:7], v[6:7], v[146:147] op_sel_hi:[1,0]
	v_pk_mul_f32 v[4:5], v[4:5], v[146:147] op_sel_hi:[1,0]
	v_pk_mul_f32 v[2:3], v[2:3], v[146:147] op_sel_hi:[1,0]
	v_pk_mul_f32 v[0:1], v[0:1], v[146:147] op_sel_hi:[1,0]

.Lad_common:
	s_waitcnt lgkmcnt(5)
	v_mfma_f32_32x32x16_bf16 v[48:63], v[202:205], v[150:153], v[48:63]
	ds_read2_b64 v[202:205], v232 offset0:76 offset1:78
	v_exp_f32_e32 v219, v80
	v_exp_f32_e32 v96, v96
	v_exp_f32_e32 v81, v81
	v_exp_f32_e32 v97, v97
	v_exp_f32_e32 v82, v82
	v_exp_f32_e32 v98, v98
	v_exp_f32_e32 v83, v83
	v_exp_f32_e32 v99, v99
	v_mfma_f32_32x32x16_bf16 v[32:47], v[206:209], v[150:153], v[32:47]
	v_add_f32_e32 v80, v96, v219
	v_exp_f32_e32 v84, v84
	v_exp_f32_e32 v100, v100
	v_add_f32_e32 v80, 0, v80
	v_add_f32_e32 v251, v97, v81
	v_exp_f32_e32 v85, v85
	v_exp_f32_e32 v101, v101
	v_add_f32_e32 v80, v251, v80
	s_waitcnt lgkmcnt(4)
	v_mfma_f32_32x32x16_bf16 v[16:31], v[210:213], v[150:153], v[16:31]
	v_add_f32_e32 v251, v98, v82
	v_exp_f32_e32 v86, v86
	v_exp_f32_e32 v102, v102
	v_add_f32_e32 v80, v251, v80
	v_add_f32_e32 v251, v99, v83
	v_exp_f32_e32 v87, v87
	v_exp_f32_e32 v103, v103
	v_add_f32_e32 v80, v251, v80
	v_mfma_f32_32x32x16_bf16 v[0:15], v[214:217], v[150:153], v[0:15]
	v_add_f32_e32 v251, v100, v84
	v_exp_f32_e32 v88, v88
	v_exp_f32_e32 v104, v104
	v_add_f32_e32 v80, v251, v80
	v_add_f32_e32 v251, v101, v85
	v_exp_f32_e32 v89, v89
	v_exp_f32_e32 v105, v105
	v_add_f32_e32 v80, v251, v80
	s_waitcnt lgkmcnt(2)
	v_mfma_f32_32x32x16_bf16 v[48:63], v[238:241], v[146:149], v[48:63]
	v_add_f32_e32 v251, v102, v86
	v_exp_f32_e32 v90, v90
	v_exp_f32_e32 v106, v106
	v_add_f32_e32 v80, v251, v80
	v_add_f32_e32 v251, v103, v87
	v_exp_f32_e32 v91, v91
	v_exp_f32_e32 v107, v107
	v_add_f32_e32 v80, v251, v80
	v_mfma_f32_32x32x16_bf16 v[32:47], v[194:197], v[146:149], v[32:47]
	v_add_f32_e32 v251, v104, v88
	v_exp_f32_e32 v92, v92
	v_exp_f32_e32 v108, v108
	v_add_f32_e32 v80, v251, v80
	v_add_f32_e32 v251, v105, v89
	v_exp_f32_e32 v93, v93
	v_exp_f32_e32 v109, v109
	v_add_f32_e32 v80, v251, v80
	s_waitcnt lgkmcnt(0)
	v_mfma_f32_32x32x16_bf16 v[16:31], v[198:201], v[146:149], v[16:31]
	v_add_f32_e32 v251, v106, v90
	v_exp_f32_e32 v94, v94
	v_exp_f32_e32 v110, v110
	v_add_f32_e32 v80, v251, v80
	v_add_f32_e32 v251, v107, v91
	v_exp_f32_e32 v95, v95
	v_exp_f32_e32 v111, v111
	v_add_f32_e32 v80, v251, v80
	v_mfma_f32_32x32x16_bf16 v[0:15], v[202:205], v[146:149], v[0:15]
	v_add_f32_e32 v251, v108, v92
	v_add_f32_e32 v80, v251, v80
	v_add_f32_e32 v251, v109, v93
	v_add_f32_e32 v80, v251, v80
	v_add_f32_e32 v251, v110, v94
	v_add_f32_e32 v80, v251, v80
	v_add_f32_e32 v251, v111, v95
	v_add_f32_e32 v80, v251, v80
	v_add_f32_e32 v80, v180, v80
	v_cvt_pk_bf16_f32 v158, v219, v81
	v_cvt_pk_bf16_f32 v159, v82, v83
	v_cvt_pk_bf16_f32 v160, v84, v85
	v_cvt_pk_bf16_f32 v161, v86, v87
	v_cvt_pk_bf16_f32 v150, v96, v97
	v_cvt_pk_bf16_f32 v151, v98, v99
	v_cvt_pk_bf16_f32 v152, v100, v101
	v_cvt_pk_bf16_f32 v153, v102, v103
	v_cvt_pk_bf16_f32 v154, v88, v89
	v_cvt_pk_bf16_f32 v155, v90, v91
	v_cvt_pk_bf16_f32 v156, v92, v93
	v_cvt_pk_bf16_f32 v157, v94, v95
	v_cvt_pk_bf16_f32 v146, v104, v105
	v_cvt_pk_bf16_f32 v147, v106, v107
	v_cvt_pk_bf16_f32 v148, v108, v109
	v_cvt_pk_bf16_f32 v149, v110, v111

.LBB0_1415:
	v_readlane_b32 s4, v252, 4
	v_readlane_b32 s5, v252, 5
	s_andn2_b64 vcc, exec, s[4:5]
	s_nop 0
	v_cndmask_b32_e64 v0, 0, 1, s[4:5]
	v_cmp_ne_u32_e64 s[44:45], 1, v0
	s_cbranch_vccnz .LBB0_1429
	s_waitcnt vmcnt(0)
	s_waitcnt vmcnt(0) lgkmcnt(0)
	s_barrier
	s_and_saveexec_b64 s[14:15], s[90:91]
	s_cbranch_execz .LBB0_1435
	s_mov_b64 s[18:19], exec
	v_mbcnt_lo_u32_b32 v0, s18, 0
	v_mbcnt_hi_u32_b32 v0, s19, v0
	v_cmp_eq_u32_e32 vcc, 0, v0
	s_and_saveexec_b64 s[16:17], vcc
	s_cbranch_execz .LBB0_1419
	s_bcnt1_i32_b64 s3, s[18:19]
	v_readlane_b32 s4, v253, 39
	v_mov_b32_e32 v1, s3
	v_readlane_b32 s5, v253, 40
	s_nop 4
	global_atomic_add v1, v129, v1, s[4:5] sc0
	buffer_inv sc1

.LBB0_1434:
	s_or_b64 exec, exec, s[16:17]
	s_waitcnt vmcnt(0)
	s_waitcnt vmcnt(0)

.LBB0_1543:
	s_and_b64 vcc, exec, s[44:45]
	s_cbranch_vccnz .LBB0_1557
	s_waitcnt vmcnt(0)
	s_waitcnt lgkmcnt(0)
	s_barrier
	s_and_saveexec_b64 s[14:15], s[90:91]
	s_cbranch_execz .LBB0_1563
	s_mov_b64 s[18:19], exec
	v_mbcnt_lo_u32_b32 v0, s18, 0
	v_mbcnt_hi_u32_b32 v0, s19, v0
	v_cmp_eq_u32_e32 vcc, 0, v0
	s_and_saveexec_b64 s[16:17], vcc
	s_cbranch_execz .LBB0_1547
	s_bcnt1_i32_b64 s4, s[18:19]
	v_mov_b32_e32 v1, s4
	v_readlane_b32 s4, v253, 39
	v_readlane_b32 s5, v253, 40
	s_nop 4
	global_atomic_add v1, v129, v1, s[4:5] sc0
	buffer_inv sc1

.LBB0_1679:
	v_readlane_b32 s4, v252, 4
	v_readlane_b32 s5, v252, 5
	s_and_b64 vcc, exec, s[4:5]
	s_cbranch_vccz .LBB0_1693
	s_waitcnt vmcnt(0)
	s_barrier
	s_and_saveexec_b64 s[14:15], s[90:91]
	s_cbranch_execz .LBB0_1699
	s_mov_b64 s[18:19], exec
	s_waitcnt vmcnt(0)
	v_mbcnt_lo_u32_b32 v0, s18, 0
	v_mbcnt_hi_u32_b32 v0, s19, v0
	v_cmp_eq_u32_e32 vcc, 0, v0
	s_and_saveexec_b64 s[16:17], vcc
	s_cbranch_execz .LBB0_1683
	s_bcnt1_i32_b64 s4, s[18:19]
	v_mov_b32_e32 v1, s4
	v_readlane_b32 s4, v253, 39
	v_readlane_b32 s5, v253, 40
	s_nop 4
	global_atomic_add v1, v129, v1, s[4:5] sc0
	buffer_inv sc1

.LBB0_1773:
	s_and_b64 vcc, exec, s[44:45]
	s_cbranch_vccnz .LBB0_1787
	s_waitcnt vmcnt(0)
	s_waitcnt vmcnt(0)
	s_barrier
	s_and_saveexec_b64 s[14:15], s[90:91]
	s_cbranch_execz .LBB0_1793
	s_mov_b64 s[18:19], exec
	v_mbcnt_lo_u32_b32 v0, s18, 0
	v_mbcnt_hi_u32_b32 v0, s19, v0
	v_cmp_eq_u32_e32 vcc, 0, v0
	s_and_saveexec_b64 s[16:17], vcc
	s_cbranch_execz .LBB0_1777
	s_bcnt1_i32_b64 s5, s[18:19]
	v_readlane_b32 s18, v253, 39
	v_mov_b32_e32 v1, s5
	v_readlane_b32 s19, v253, 40
	s_nop 4
	global_atomic_add v1, v129, v1, s[18:19] sc0
	buffer_inv sc1

.LBB0_1901:
	s_and_b64 vcc, exec, s[44:45]
	s_cbranch_vccnz .LBB0_1915
	s_waitcnt vmcnt(0)
	s_waitcnt vmcnt(0) lgkmcnt(0)
	s_barrier
	s_and_saveexec_b64 s[14:15], s[90:91]
	s_cbranch_execz .LBB0_1921
	s_mov_b64 s[18:19], exec
	v_mbcnt_lo_u32_b32 v0, s18, 0
	v_mbcnt_hi_u32_b32 v0, s19, v0
	v_cmp_eq_u32_e32 vcc, 0, v0
	s_and_saveexec_b64 s[16:17], vcc
	s_cbranch_execz .LBB0_1905
	s_bcnt1_i32_b64 s3, s[18:19]
	v_readlane_b32 s4, v253, 39
	v_mov_b32_e32 v1, s3
	v_readlane_b32 s5, v253, 40
	s_nop 4
	global_atomic_add v1, v129, v1, s[4:5] sc0
	buffer_inv sc1
